# back-edge rotation into the light phase: loop bookkeeping and the next-tile pointer select block moved from the head of the heaviest loader segment to behind the last phase's stage loads (skipped on t
# baseline (speedup 1.0000x reference)
; #define G_STAGE(bufoff, gbase) do { _Pragma("unroll") for (int _i = 0; _i < 2; ++_i) \
;         __builtin_amdgcn_global_load_lds((const unsigned*)((const char*)(gbase) + voff[_i]), (LAS unsigned*)(lds + (bufoff) + ldsw + _i * 8192), 16, 0, 0); } while (0)
; #define G_LDA(dst, b, h) do { _Pragma("unroll") for (int m = 0; m < 4; ++m) _Pragma("unroll") for (int k = 0; k < 2; ++k) dst[m][k] = *(const LAS bf16x8*)(lds + G_SA(b, h) + aoff + m * 2048 + k * 1024); } while (0)
; #define G_LDB(dst, b, h) do { _Pragma("unroll") for (int n = 0; n < 2; ++n) _Pragma("unroll") for (int k = 0; k < 2; ++k) dst[n][k] = *(const LAS bf16x8*)(lds + G_SB(b, h) + boff + n * 2048 + k * 1024); } while (0)
; #define G_MMA(ai, bj, At, Bt) do { __builtin_amdgcn_s_setprio(1); _Pragma("unroll") for (int m = 0; m < 4; ++m) _Pragma("unroll") for (int n = 0; n < 2; ++n) _Pragma("unroll") for (int k = 0; k < 2; ++k) \
;         acc[ai][bj][m][n] = MFMA16(Bt[n][k], At[m][k], acc[ai][bj][m][n]); __builtin_amdgcn_s_setprio(0); } while (0)
; #define G_WAIT_V(n) asm volatile("s_waitcnt vmcnt(" #n ")" ::: "memory")
; #define G_WAIT_L(n) asm volatile("s_waitcnt lgkmcnt(" #n ")" ::: "memory")
; #define G_BAR __builtin_amdgcn_s_barrier()
; #define G_SCHED __builtin_amdgcn_sched_barrier(0)
; template <class Epi>
; __device__ __forceinline__ void gemm_phase(LAS unsigned char* lds, const bf16_t* Ag, const bf16_t* Btg, const int K, const int nM, const int nN, const Epi& E) {
;     ...
;             G_LDB(B0, 0, 0); G_SCHED; G_LDA(At, 0, 0); G_STAGE(G_SA(1, 1), a1 + hstep);
;             G_WAIT_L(8); G_BAR; G_WAIT_L(0); G_MMA(0, 0, At, B0); G_BAR; G_SCHED;
;             G_LDB(B1, 0, 1); G_STAGE(G_SB(0, 0), b2);
;             G_BAR; G_WAIT_L(0); G_MMA(0, 1, At, B1); G_BAR;
;             G_LDA(At, 0, 1); G_STAGE(G_SA(0, 0), a2);
;             G_BAR; G_WAIT_L(0); G_MMA(1, 0, At, B0); G_BAR; G_SCHED;
;             G_STAGE(G_SB(0, 1), b2 + hstep);
;             G_WAIT_V(6); G_BAR; G_MMA(1, 1, At, B1); G_BAR;
.LmainW_78:
	ds_read_b128 v[124:127], v217
	ds_read_b128 v[128:131], v217 offset:1024
	ds_read_b128 v[132:135], v217 offset:2048
	ds_read_b128 v[136:139], v217 offset:3072
	s_add_i32 m0, s58, 0xc000
	ds_read_b128 v[140:143], v186
	ds_read_b128 v[148:151], v186 offset:1024
	ds_read_b128 v[152:155], v186 offset:2048
	ds_read_b128 v[156:159], v186 offset:3072
	ds_read_b128 v[188:191], v186 offset:4096
	ds_read_b128 v[192:195], v186 offset:5120
	ds_read_b128 v[222:225], v186 offset:6144
	global_load_lds_dwordx4 v170, s[50:51]
	s_add_i32 m0, s58, 0xe000
	ds_read_b128 v[226:229], v186 offset:7168
	global_load_lds_dwordx4 v168, s[50:51]
	s_waitcnt lgkmcnt(8)
	s_barrier
	s_waitcnt lgkmcnt(0)
	s_waitcnt lgkmcnt(0)
	v_mfma_f32_16x16x32_bf16 v[164:167], v[124:127], v[140:143], v[164:167]
	v_mfma_f32_16x16x32_bf16 v[160:163], v[132:135], v[140:143], v[160:163]
	v_mfma_f32_16x16x32_bf16 v[116:119], v[124:127], v[152:155], v[116:119]
	v_mfma_f32_16x16x32_bf16 v[112:115], v[132:135], v[152:155], v[112:115]
	v_mfma_f32_16x16x32_bf16 v[100:103], v[124:127], v[188:191], v[100:103]
	v_mfma_f32_16x16x32_bf16 v[96:99], v[132:135], v[188:191], v[96:99]
	v_mfma_f32_16x16x32_bf16 v[84:87], v[124:127], v[222:225], v[84:87]
	v_mfma_f32_16x16x32_bf16 v[80:83], v[132:135], v[222:225], v[80:83]
	v_mfma_f32_16x16x32_bf16 v[164:167], v[128:131], v[148:151], v[164:167]
	v_mfma_f32_16x16x32_bf16 v[160:163], v[136:139], v[148:151], v[160:163]
	v_mfma_f32_16x16x32_bf16 v[116:119], v[128:131], v[156:159], v[116:119]
	v_mfma_f32_16x16x32_bf16 v[112:115], v[136:139], v[156:159], v[112:115]
	v_mfma_f32_16x16x32_bf16 v[100:103], v[128:131], v[192:195], v[100:103]
	v_mfma_f32_16x16x32_bf16 v[96:99], v[136:139], v[192:195], v[96:99]
	v_mfma_f32_16x16x32_bf16 v[84:87], v[128:131], v[226:229], v[84:87]
	v_mfma_f32_16x16x32_bf16 v[80:83], v[136:139], v[226:229], v[80:83]
	s_barrier
	ds_read_b128 v[230:233], v217 offset:16384
	ds_read_b128 v[234:237], v217 offset:17408
	s_add_i32 m0, s57, 0x10000
	ds_read_b128 v[238:241], v217 offset:18432
	global_load_lds_dwordx4 v0, s[52:53]
	s_add_i32 m0, s57, 0x12000
	ds_read_b128 v[242:245], v217 offset:19456
	global_load_lds_dwordx4 v2, s[52:53]
	s_barrier
	s_waitcnt lgkmcnt(0)
	s_waitcnt lgkmcnt(0)
	v_mfma_f32_16x16x32_bf16 v[144:147], v[230:233], v[140:143], v[144:147]
	v_mfma_f32_16x16x32_bf16 v[120:123], v[238:241], v[140:143], v[120:123]
	v_mfma_f32_16x16x32_bf16 v[108:111], v[230:233], v[152:155], v[108:111]
	v_mfma_f32_16x16x32_bf16 v[104:107], v[238:241], v[152:155], v[104:107]
	v_mfma_f32_16x16x32_bf16 v[92:95], v[230:233], v[188:191], v[92:95]
	v_mfma_f32_16x16x32_bf16 v[88:91], v[238:241], v[188:191], v[88:91]
	v_mfma_f32_16x16x32_bf16 v[76:79], v[230:233], v[222:225], v[76:79]
	v_mfma_f32_16x16x32_bf16 v[72:75], v[238:241], v[222:225], v[72:75]
	v_mfma_f32_16x16x32_bf16 v[144:147], v[234:237], v[148:151], v[144:147]
	v_mfma_f32_16x16x32_bf16 v[120:123], v[242:245], v[148:151], v[120:123]
	v_mfma_f32_16x16x32_bf16 v[108:111], v[234:237], v[156:159], v[108:111]
	v_mfma_f32_16x16x32_bf16 v[104:107], v[242:245], v[156:159], v[104:107]
	v_mfma_f32_16x16x32_bf16 v[92:95], v[234:237], v[192:195], v[92:95]
	v_mfma_f32_16x16x32_bf16 v[88:91], v[242:245], v[192:195], v[88:91]
	v_mfma_f32_16x16x32_bf16 v[76:79], v[234:237], v[226:229], v[76:79]
	v_mfma_f32_16x16x32_bf16 v[72:75], v[242:245], v[226:229], v[72:75]
	s_mov_b32 m0, s58
	s_barrier
	ds_read_b128 v[140:143], v186 offset:16384
	ds_read_b128 v[148:151], v186 offset:17408
	ds_read_b128 v[152:155], v186 offset:18432
	ds_read_b128 v[156:159], v186 offset:19456
	ds_read_b128 v[188:191], v186 offset:20480
	ds_read_b128 v[192:195], v186 offset:21504
	ds_read_b128 v[222:225], v186 offset:22528
	global_load_lds_dwordx4 v0, s[54:55]
	s_mov_b32 m0, s59
	ds_read_b128 v[226:229], v186 offset:23552
	global_load_lds_dwordx4 v2, s[54:55]
	s_barrier
	s_waitcnt lgkmcnt(0)
	s_waitcnt lgkmcnt(0)
	v_mfma_f32_16x16x32_bf16 v[60:63], v[124:127], v[140:143], v[60:63]
	v_mfma_f32_16x16x32_bf16 v[56:59], v[132:135], v[140:143], v[56:59]
	v_mfma_f32_16x16x32_bf16 v[44:47], v[124:127], v[152:155], v[44:47]
	v_mfma_f32_16x16x32_bf16 v[40:43], v[132:135], v[152:155], v[40:43]
	v_mfma_f32_16x16x32_bf16 v[28:31], v[124:127], v[188:191], v[28:31]
	v_mfma_f32_16x16x32_bf16 v[24:27], v[132:135], v[188:191], v[24:27]
	v_mfma_f32_16x16x32_bf16 v[12:15], v[124:127], v[222:225], v[12:15]
	v_mfma_f32_16x16x32_bf16 v[8:11], v[132:135], v[222:225], v[8:11]
	v_mfma_f32_16x16x32_bf16 v[60:63], v[128:131], v[148:151], v[60:63]
	v_mfma_f32_16x16x32_bf16 v[56:59], v[136:139], v[148:151], v[56:59]
	v_mfma_f32_16x16x32_bf16 v[44:47], v[128:131], v[156:159], v[44:47]
	v_mfma_f32_16x16x32_bf16 v[40:43], v[136:139], v[156:159], v[40:43]
	v_mfma_f32_16x16x32_bf16 v[28:31], v[128:131], v[192:195], v[28:31]
	v_mfma_f32_16x16x32_bf16 v[24:27], v[136:139], v[192:195], v[24:27]
	v_mfma_f32_16x16x32_bf16 v[12:15], v[128:131], v[226:229], v[12:15]
	v_mfma_f32_16x16x32_bf16 v[8:11], v[136:139], v[226:229], v[8:11]
	s_barrier
	s_add_u32 s74, s52, 0x40000
	s_addc_u32 s75, s53, 0
	s_add_i32 m0, s57, 0x14000
	s_nop 0
	global_load_lds_dwordx4 v0, s[74:75]
	s_add_i32 m0, s57, 0x16000
	s_nop 0
	global_load_lds_dwordx4 v2, s[74:75]
	s_waitcnt vmcnt(6)
	s_barrier
; #define G_STAGE(bufoff, gbase) do { _Pragma("unroll") for (int _i = 0; _i < 2; ++_i) \
;         __builtin_amdgcn_global_load_lds((const unsigned*)((const char*)(gbase) + voff[_i]), (LAS unsigned*)(lds + (bufoff) + ldsw + _i * 8192), 16, 0, 0); } while (0)
; #define G_LDA(dst, b, h) do { _Pragma("unroll") for (int m = 0; m < 4; ++m) _Pragma("unroll") for (int k = 0; k < 2; ++k) dst[m][k] = *(const LAS bf16x8*)(lds + G_SA(b, h) + aoff + m * 2048 + k * 1024); } while (0)
; #define G_LDB(dst, b, h) do { _Pragma("unroll") for (int n = 0; n < 2; ++n) _Pragma("unroll") for (int k = 0; k < 2; ++k) dst[n][k] = *(const LAS bf16x8*)(lds + G_SB(b, h) + boff + n * 2048 + k * 1024); } while (0)
; #define G_MMA(ai, bj, At, Bt) do { __builtin_amdgcn_s_setprio(1); _Pragma("unroll") for (int m = 0; m < 4; ++m) _Pragma("unroll") for (int n = 0; n < 2; ++n) _Pragma("unroll") for (int k = 0; k < 2; ++k) \
;         acc[ai][bj][m][n] = MFMA16(Bt[n][k], At[m][k], acc[ai][bj][m][n]); __builtin_amdgcn_s_setprio(0); } while (0)
; #define G_WAIT_V(n) asm volatile("s_waitcnt vmcnt(" #n ")" ::: "memory")
; #define G_WAIT_L(n) asm volatile("s_waitcnt lgkmcnt(" #n ")" ::: "memory")
; #define G_BAR __builtin_amdgcn_s_barrier()
; #define G_SCHED __builtin_amdgcn_sched_barrier(0)
; template <class Epi>
; __device__ __forceinline__ void gemm_phase(LAS unsigned char* lds, const bf16_t* Ag, const bf16_t* Btg, const int K, const int nM, const int nN, const Epi& E) {
;     ...
;         for (int t = 0; t < nt; t += 2) {
;             const bool last = (t == nt - 2);
;             const char* a1 = cA + (size_t)(t + 1) * kstep;
;             const char* a2 = last ? nA : cA + (size_t)(t + 2) * kstep; const char* b2 = last ? nB : cB + (size_t)(t + 2) * kstep;
;             const char* a3 = a2 + kstep; const char* b3 = b2 + kstep;
;     ...
;             G_WAIT_V(6); G_BAR; G_MMA(1, 1, At, B1); G_BAR;
;             G_LDB(B0, 1, 0); G_SCHED; G_LDA(At, 1, 0); G_STAGE(G_SA(0, 1), a2 + hstep);
;             G_WAIT_L(8); G_BAR; G_WAIT_L(0); G_MMA(0, 0, At, B0); G_BAR; G_SCHED;
;             G_LDB(B1, 1, 1); G_STAGE(G_SB(1, 0), b3);
;             G_BAR; G_WAIT_L(0); G_MMA(0, 1, At, B1); G_BAR;
;             G_LDA(At, 1, 1); G_STAGE(G_SA(1, 0), a3);
;             G_BAR; G_WAIT_L(0); G_MMA(1, 0, At, B0); G_BAR; G_SCHED;
;             G_STAGE(G_SB(1, 1), b3 + hstep);
	v_mfma_f32_16x16x32_bf16 v[68:71], v[230:233], v[140:143], v[68:71]
	v_mfma_f32_16x16x32_bf16 v[64:67], v[238:241], v[140:143], v[64:67]
	v_mfma_f32_16x16x32_bf16 v[52:55], v[230:233], v[152:155], v[52:55]
	v_mfma_f32_16x16x32_bf16 v[48:51], v[238:241], v[152:155], v[48:51]
	v_mfma_f32_16x16x32_bf16 v[36:39], v[230:233], v[188:191], v[36:39]
	v_mfma_f32_16x16x32_bf16 v[32:35], v[238:241], v[188:191], v[32:35]
	v_mfma_f32_16x16x32_bf16 v[20:23], v[230:233], v[222:225], v[20:23]
	v_mfma_f32_16x16x32_bf16 v[16:19], v[238:241], v[222:225], v[16:19]
	v_mfma_f32_16x16x32_bf16 v[68:71], v[234:237], v[148:151], v[68:71]
	v_mfma_f32_16x16x32_bf16 v[64:67], v[242:245], v[148:151], v[64:67]
	v_mfma_f32_16x16x32_bf16 v[52:55], v[234:237], v[156:159], v[52:55]
	v_mfma_f32_16x16x32_bf16 v[48:51], v[242:245], v[156:159], v[48:51]
	v_mfma_f32_16x16x32_bf16 v[36:39], v[234:237], v[192:195], v[36:39]
	v_mfma_f32_16x16x32_bf16 v[32:35], v[242:245], v[192:195], v[32:35]
	v_mfma_f32_16x16x32_bf16 v[20:23], v[234:237], v[226:229], v[20:23]
	v_mfma_f32_16x16x32_bf16 v[16:19], v[242:245], v[226:229], v[16:19]
	s_barrier
	ds_read_b128 v[124:127], v217 offset:32768
	ds_read_b128 v[128:131], v217 offset:33792
	ds_read_b128 v[132:135], v217 offset:34816
	ds_read_b128 v[136:139], v217 offset:35840
	s_add_u32 s54, s54, 0x40000
	s_addc_u32 s55, s55, 0
	s_mov_b32 m0, s60
	ds_read_b128 v[140:143], v186 offset:32768
	ds_read_b128 v[148:151], v186 offset:33792
	ds_read_b128 v[152:155], v186 offset:34816
	ds_read_b128 v[156:159], v186 offset:35840
	ds_read_b128 v[188:191], v186 offset:36864
	ds_read_b128 v[192:195], v186 offset:37888
	ds_read_b128 v[222:225], v186 offset:38912
	global_load_lds_dwordx4 v0, s[54:55]
	s_mov_b32 m0, s61
	ds_read_b128 v[226:229], v186 offset:39936
	global_load_lds_dwordx4 v2, s[54:55]
	s_waitcnt lgkmcnt(8)
	s_barrier
	s_waitcnt lgkmcnt(0)
	s_waitcnt lgkmcnt(0)
	v_mfma_f32_16x16x32_bf16 v[164:167], v[124:127], v[140:143], v[164:167]
	v_mfma_f32_16x16x32_bf16 v[160:163], v[132:135], v[140:143], v[160:163]
	v_mfma_f32_16x16x32_bf16 v[116:119], v[124:127], v[152:155], v[116:119]
	v_mfma_f32_16x16x32_bf16 v[112:115], v[132:135], v[152:155], v[112:115]
	v_mfma_f32_16x16x32_bf16 v[100:103], v[124:127], v[188:191], v[100:103]
	v_mfma_f32_16x16x32_bf16 v[96:99], v[132:135], v[188:191], v[96:99]
	v_mfma_f32_16x16x32_bf16 v[84:87], v[124:127], v[222:225], v[84:87]
	v_mfma_f32_16x16x32_bf16 v[80:83], v[132:135], v[222:225], v[80:83]
	v_mfma_f32_16x16x32_bf16 v[164:167], v[128:131], v[148:151], v[164:167]
	v_mfma_f32_16x16x32_bf16 v[160:163], v[136:139], v[148:151], v[160:163]
	v_mfma_f32_16x16x32_bf16 v[116:119], v[128:131], v[156:159], v[116:119]
	v_mfma_f32_16x16x32_bf16 v[112:115], v[136:139], v[156:159], v[112:115]
	v_mfma_f32_16x16x32_bf16 v[100:103], v[128:131], v[192:195], v[100:103]
	v_mfma_f32_16x16x32_bf16 v[96:99], v[136:139], v[192:195], v[96:99]
	v_mfma_f32_16x16x32_bf16 v[84:87], v[128:131], v[226:229], v[84:87]
	v_mfma_f32_16x16x32_bf16 v[80:83], v[136:139], v[226:229], v[80:83]
	s_barrier
	s_add_i32 s26, 0, 0x1c000
	s_add_i32 m0, s57, 0x18000
	ds_read_b128 v[230:233], v217 offset:49152
	ds_read_b128 v[234:237], v217 offset:50176
	ds_read_b128 v[238:241], v217 offset:51200
	ds_read_b128 v[242:245], v217 offset:52224
	s_add_u32 s98, s52, 0x80
	s_addc_u32 s99, s53, 0
	global_load_lds_dwordx4 v0, s[98:99]
	s_add_i32 m0, s57, 0x1a000
	s_nop 0
	global_load_lds_dwordx4 v2, s[98:99]
	s_barrier
	s_waitcnt lgkmcnt(0)
	s_waitcnt lgkmcnt(0)
	v_mfma_f32_16x16x32_bf16 v[144:147], v[230:233], v[140:143], v[144:147]
	v_mfma_f32_16x16x32_bf16 v[120:123], v[238:241], v[140:143], v[120:123]
	v_mfma_f32_16x16x32_bf16 v[108:111], v[230:233], v[152:155], v[108:111]
	v_mfma_f32_16x16x32_bf16 v[104:107], v[238:241], v[152:155], v[104:107]
	v_mfma_f32_16x16x32_bf16 v[92:95], v[230:233], v[188:191], v[92:95]
	v_mfma_f32_16x16x32_bf16 v[88:91], v[238:241], v[188:191], v[88:91]
	v_mfma_f32_16x16x32_bf16 v[76:79], v[230:233], v[222:225], v[76:79]
	v_mfma_f32_16x16x32_bf16 v[72:75], v[238:241], v[222:225], v[72:75]
	v_mfma_f32_16x16x32_bf16 v[144:147], v[234:237], v[148:151], v[144:147]
	v_mfma_f32_16x16x32_bf16 v[120:123], v[242:245], v[148:151], v[120:123]
	v_mfma_f32_16x16x32_bf16 v[108:111], v[234:237], v[156:159], v[108:111]
	v_mfma_f32_16x16x32_bf16 v[104:107], v[242:245], v[156:159], v[104:107]
	v_mfma_f32_16x16x32_bf16 v[92:95], v[234:237], v[192:195], v[92:95]
	v_mfma_f32_16x16x32_bf16 v[88:91], v[242:245], v[192:195], v[88:91]
	v_mfma_f32_16x16x32_bf16 v[76:79], v[234:237], v[226:229], v[76:79]
	v_mfma_f32_16x16x32_bf16 v[72:75], v[242:245], v[226:229], v[72:75]
	s_mov_b32 m0, s62
	s_barrier
	ds_read_b128 v[140:143], v186 offset:49152
	ds_read_b128 v[148:151], v186 offset:50176
	ds_read_b128 v[152:155], v186 offset:51200
	ds_read_b128 v[156:159], v186 offset:52224
	ds_read_b128 v[188:191], v186 offset:53248
	ds_read_b128 v[192:195], v186 offset:54272
	ds_read_b128 v[222:225], v186 offset:55296
	ds_read_b128 v[226:229], v186 offset:56320
	s_add_u32 s98, s54, 0xfffc0080
	s_addc_u32 s99, s55, -1
	global_load_lds_dwordx4 v0, s[98:99]
	s_mov_b32 m0, s63
	s_nop 0
	global_load_lds_dwordx4 v2, s[98:99]
	s_barrier
	s_waitcnt lgkmcnt(0)
	s_waitcnt lgkmcnt(0)
	v_mfma_f32_16x16x32_bf16 v[60:63], v[124:127], v[140:143], v[60:63]
	v_mfma_f32_16x16x32_bf16 v[56:59], v[132:135], v[140:143], v[56:59]
	v_mfma_f32_16x16x32_bf16 v[44:47], v[124:127], v[152:155], v[44:47]
	v_mfma_f32_16x16x32_bf16 v[40:43], v[132:135], v[152:155], v[40:43]
	v_mfma_f32_16x16x32_bf16 v[28:31], v[124:127], v[188:191], v[28:31]
	v_mfma_f32_16x16x32_bf16 v[24:27], v[132:135], v[188:191], v[24:27]
	v_mfma_f32_16x16x32_bf16 v[12:15], v[124:127], v[222:225], v[12:15]
	v_mfma_f32_16x16x32_bf16 v[8:11], v[132:135], v[222:225], v[8:11]
	v_mfma_f32_16x16x32_bf16 v[60:63], v[128:131], v[148:151], v[60:63]
	v_mfma_f32_16x16x32_bf16 v[56:59], v[136:139], v[148:151], v[56:59]
	v_mfma_f32_16x16x32_bf16 v[44:47], v[128:131], v[156:159], v[44:47]
	v_mfma_f32_16x16x32_bf16 v[40:43], v[136:139], v[156:159], v[40:43]
	v_mfma_f32_16x16x32_bf16 v[28:31], v[128:131], v[192:195], v[28:31]
	v_mfma_f32_16x16x32_bf16 v[24:27], v[136:139], v[192:195], v[24:27]
	v_mfma_f32_16x16x32_bf16 v[12:15], v[128:131], v[226:229], v[12:15]
	v_mfma_f32_16x16x32_bf16 v[8:11], v[136:139], v[226:229], v[8:11]
	s_barrier
	s_add_u32 s52, s52, 0x40080
	s_addc_u32 s53, s53, 0
	s_add_i32 s12, s26, s57
	s_add_i32 m0, s57, 0x1c000
	s_nop 0
	global_load_lds_dwordx4 v0, s[52:53]
	s_add_i32 m0, s57, 0x1e000
	s_nop 0
	global_load_lds_dwordx4 v2, s[52:53]
	s_add_i32 s73, s73, 2
	s_add_u32 s71, s71, 0x100
	s_addc_u32 s72, s72, 0
	s_add_u32 s50, s50, 0x100
	s_addc_u32 s51, s51, 0
	s_cmp_gt_u32 s73, 13
	s_cbranch_scc1 .LrotX_78
	s_cmp_lg_u32 s73, 12
	s_cselect_b64 s[52:53], -1, 0
	s_add_u32 s12, s50, 0xfffc0080
	s_addc_u32 s26, s51, -1
	s_and_b64 s[52:53], s[52:53], exec
	s_cselect_b32 s55, s26, s43
	s_cselect_b32 s54, s12, s42
	s_cselect_b32 s53, s72, s15
	s_cselect_b32 s52, s71, s69
;     __device__ __forceinline__ void prep(int pm, int par, LAS unsigned char* lds) const { if (fold) prep_rowstats(stat, pm, par, lds); }
;     __device__ __forceinline__ void prep(int pm, int par, LAS unsigned char* lds) const { if (!ident) prep_rowstats(stat, pm, par, lds); }
;     __device__ __forceinline__ void prep(int pm, int par, LAS unsigned char* lds) const { prep_rowstats(stat, pm, par, lds); }
; #define G_STAGE(bufoff, gbase) do { _Pragma("unroll") for (int _i = 0; _i < 2; ++_i) \
;         __builtin_amdgcn_global_load_lds((const unsigned*)((const char*)(gbase) + voff[_i]), (LAS unsigned*)(lds + (bufoff) + ldsw + _i * 8192), 16, 0, 0); } while (0)
; #define G_MMA(ai, bj, At, Bt) do { __builtin_amdgcn_s_setprio(1); _Pragma("unroll") for (int m = 0; m < 4; ++m) _Pragma("unroll") for (int n = 0; n < 2; ++n) _Pragma("unroll") for (int k = 0; k < 2; ++k) \
;         acc[ai][bj][m][n] = MFMA16(Bt[n][k], At[m][k], acc[ai][bj][m][n]); __builtin_amdgcn_s_setprio(0); } while (0)
; #define G_WAIT_V(n) asm volatile("s_waitcnt vmcnt(" #n ")" ::: "memory")
; #define G_BAR __builtin_amdgcn_s_barrier()
; template <class Epi>
; __device__ __forceinline__ void gemm_phase(LAS unsigned char* lds, const bf16_t* Ag, const bf16_t* Btg, const int K, const int nM, const int nN, const Epi& E) {
;     ...
;         for (int t = 0; t < nt; t += 2) {
;             const bool last = (t == nt - 2);
;             const char* a1 = cA + (size_t)(t + 1) * kstep;
;             const char* a2 = last ? nA : cA + (size_t)(t + 2) * kstep; const char* b2 = last ? nB : cB + (size_t)(t + 2) * kstep;
;             const char* a3 = a2 + kstep; const char* b3 = b2 + kstep;
;             if (last && has_next && pmn != pm) E.prep(pmn, par ^ 1, lds);
;     ...
;             G_STAGE(G_SB(1, 1), b3 + hstep);
;             G_WAIT_V(6); G_BAR; G_MMA(1, 1, At, B1); G_BAR;
;         }
.LrotX_78:
	s_waitcnt vmcnt(6)
	s_barrier
	v_mfma_f32_16x16x32_bf16 v[68:71], v[230:233], v[140:143], v[68:71]
	v_mfma_f32_16x16x32_bf16 v[64:67], v[238:241], v[140:143], v[64:67]
	v_mfma_f32_16x16x32_bf16 v[52:55], v[230:233], v[152:155], v[52:55]
	v_mfma_f32_16x16x32_bf16 v[48:51], v[238:241], v[152:155], v[48:51]
	v_mfma_f32_16x16x32_bf16 v[36:39], v[230:233], v[188:191], v[36:39]
	v_mfma_f32_16x16x32_bf16 v[32:35], v[238:241], v[188:191], v[32:35]
	v_mfma_f32_16x16x32_bf16 v[20:23], v[230:233], v[222:225], v[20:23]
	v_mfma_f32_16x16x32_bf16 v[16:19], v[238:241], v[222:225], v[16:19]
	v_mfma_f32_16x16x32_bf16 v[68:71], v[234:237], v[148:151], v[68:71]
	v_mfma_f32_16x16x32_bf16 v[64:67], v[242:245], v[148:151], v[64:67]
	v_mfma_f32_16x16x32_bf16 v[52:55], v[234:237], v[156:159], v[52:55]
	v_mfma_f32_16x16x32_bf16 v[48:51], v[242:245], v[156:159], v[48:51]
	v_mfma_f32_16x16x32_bf16 v[36:39], v[234:237], v[192:195], v[36:39]
	v_mfma_f32_16x16x32_bf16 v[32:35], v[242:245], v[192:195], v[32:35]
	v_mfma_f32_16x16x32_bf16 v[20:23], v[234:237], v[226:229], v[20:23]
	v_mfma_f32_16x16x32_bf16 v[16:19], v[242:245], v[226:229], v[16:19]
	s_cmp_gt_u32 s73, 13
	s_barrier
	s_cbranch_scc1 .LBB0_82
	s_cmp_lg_u32 s73, 12
	s_cbranch_scc1 .LmainW_78

; #define G_STAGE(bufoff, gbase) do { _Pragma("unroll") for (int _i = 0; _i < 2; ++_i) \
;         __builtin_amdgcn_global_load_lds((const unsigned*)((const char*)(gbase) + voff[_i]), (LAS unsigned*)(lds + (bufoff) + ldsw + _i * 8192), 16, 0, 0); } while (0)
; #define G_LDA(dst, b, h) do { _Pragma("unroll") for (int m = 0; m < 4; ++m) _Pragma("unroll") for (int k = 0; k < 2; ++k) dst[m][k] = *(const LAS bf16x8*)(lds + G_SA(b, h) + aoff + m * 2048 + k * 1024); } while (0)
; #define G_LDB(dst, b, h) do { _Pragma("unroll") for (int n = 0; n < 2; ++n) _Pragma("unroll") for (int k = 0; k < 2; ++k) dst[n][k] = *(const LAS bf16x8*)(lds + G_SB(b, h) + boff + n * 2048 + k * 1024); } while (0)
; #define G_MMA(ai, bj, At, Bt) do { __builtin_amdgcn_s_setprio(1); _Pragma("unroll") for (int m = 0; m < 4; ++m) _Pragma("unroll") for (int n = 0; n < 2; ++n) _Pragma("unroll") for (int k = 0; k < 2; ++k) \
;         acc[ai][bj][m][n] = MFMA16(Bt[n][k], At[m][k], acc[ai][bj][m][n]); __builtin_amdgcn_s_setprio(0); } while (0)
; #define G_WAIT_V(n) asm volatile("s_waitcnt vmcnt(" #n ")" ::: "memory")
; #define G_WAIT_L(n) asm volatile("s_waitcnt lgkmcnt(" #n ")" ::: "memory")
; #define G_BAR __builtin_amdgcn_s_barrier()
; #define G_SCHED __builtin_amdgcn_sched_barrier(0)
; template <class Epi>
; __device__ __forceinline__ void gemm_phase(LAS unsigned char* lds, const bf16_t* Ag, const bf16_t* Btg, const int K, const int nM, const int nN, const Epi& E) {
;     ...
;             G_LDB(B0, 0, 0); G_SCHED; G_LDA(At, 0, 0); G_STAGE(G_SA(1, 1), a1 + hstep);
;             G_WAIT_L(8); G_BAR; G_WAIT_L(0); G_MMA(0, 0, At, B0); G_BAR; G_SCHED;
;             G_LDB(B1, 0, 1); G_STAGE(G_SB(0, 0), b2);
;             G_BAR; G_WAIT_L(0); G_MMA(0, 1, At, B1); G_BAR;
;             G_LDA(At, 0, 1); G_STAGE(G_SA(0, 0), a2);
;             G_BAR; G_WAIT_L(0); G_MMA(1, 0, At, B0); G_BAR; G_SCHED;
;             G_STAGE(G_SB(0, 1), b2 + hstep);
;             G_WAIT_V(6); G_BAR; G_MMA(1, 1, At, B1); G_BAR;
.LmainW_153:
	ds_read_b128 v[144:147], v217
	ds_read_b128 v[148:151], v217 offset:1024
	ds_read_b128 v[152:155], v217 offset:2048
	ds_read_b128 v[156:159], v217 offset:3072
	s_add_i32 m0, s72, 0xc000
	ds_read_b128 v[160:163], v230
	ds_read_b128 v[164:167], v230 offset:1024
	ds_read_b128 v[168:171], v230 offset:2048
	ds_read_b128 v[172:175], v230 offset:3072
	ds_read_b128 v[180:183], v230 offset:4096
	ds_read_b128 v[184:187], v230 offset:5120
	ds_read_b128 v[188:191], v230 offset:6144
	global_load_lds_dwordx4 v138, s[64:65]
	s_add_i32 m0, s72, 0xe000
	ds_read_b128 v[192:195], v230 offset:7168
	global_load_lds_dwordx4 v136, s[64:65]
	s_waitcnt lgkmcnt(8)
	s_barrier
	s_waitcnt lgkmcnt(0)
	s_waitcnt lgkmcnt(0)
	v_mfma_f32_16x16x32_bf16 v[132:135], v[144:147], v[160:163], v[132:135]
	v_mfma_f32_16x16x32_bf16 v[128:131], v[152:155], v[160:163], v[128:131]
	v_mfma_f32_16x16x32_bf16 v[116:119], v[144:147], v[168:171], v[116:119]
	v_mfma_f32_16x16x32_bf16 v[112:115], v[152:155], v[168:171], v[112:115]
	v_mfma_f32_16x16x32_bf16 v[100:103], v[144:147], v[180:183], v[100:103]
	v_mfma_f32_16x16x32_bf16 v[96:99], v[152:155], v[180:183], v[96:99]
	v_mfma_f32_16x16x32_bf16 v[84:87], v[144:147], v[188:191], v[84:87]
	v_mfma_f32_16x16x32_bf16 v[80:83], v[152:155], v[188:191], v[80:83]
	v_mfma_f32_16x16x32_bf16 v[132:135], v[148:151], v[164:167], v[132:135]
	v_mfma_f32_16x16x32_bf16 v[128:131], v[156:159], v[164:167], v[128:131]
	v_mfma_f32_16x16x32_bf16 v[116:119], v[148:151], v[172:175], v[116:119]
	v_mfma_f32_16x16x32_bf16 v[112:115], v[156:159], v[172:175], v[112:115]
	v_mfma_f32_16x16x32_bf16 v[100:103], v[148:151], v[184:187], v[100:103]
	v_mfma_f32_16x16x32_bf16 v[96:99], v[156:159], v[184:187], v[96:99]
	v_mfma_f32_16x16x32_bf16 v[84:87], v[148:151], v[192:195], v[84:87]
	v_mfma_f32_16x16x32_bf16 v[80:83], v[156:159], v[192:195], v[80:83]
	s_barrier
	s_add_i32 m0, s21, 0x10000
	ds_read_b128 v[232:235], v217 offset:16384
	ds_read_b128 v[236:239], v217 offset:17408
	ds_read_b128 v[240:243], v217 offset:18432
	global_load_lds_dwordx4 v0, s[68:69]
	s_add_i32 m0, s21, 0x12000
	ds_read_b128 v[244:247], v217 offset:19456
	global_load_lds_dwordx4 v2, s[68:69]
	s_barrier
	s_waitcnt lgkmcnt(0)
	s_waitcnt lgkmcnt(0)
	v_mfma_f32_16x16x32_bf16 v[124:127], v[232:235], v[160:163], v[124:127]
	v_mfma_f32_16x16x32_bf16 v[120:123], v[240:243], v[160:163], v[120:123]
	v_mfma_f32_16x16x32_bf16 v[108:111], v[232:235], v[168:171], v[108:111]
	v_mfma_f32_16x16x32_bf16 v[104:107], v[240:243], v[168:171], v[104:107]
	v_mfma_f32_16x16x32_bf16 v[92:95], v[232:235], v[180:183], v[92:95]
	v_mfma_f32_16x16x32_bf16 v[88:91], v[240:243], v[180:183], v[88:91]
	v_mfma_f32_16x16x32_bf16 v[76:79], v[232:235], v[188:191], v[76:79]
	v_mfma_f32_16x16x32_bf16 v[72:75], v[240:243], v[188:191], v[72:75]
	v_mfma_f32_16x16x32_bf16 v[124:127], v[236:239], v[164:167], v[124:127]
	v_mfma_f32_16x16x32_bf16 v[120:123], v[244:247], v[164:167], v[120:123]
	v_mfma_f32_16x16x32_bf16 v[108:111], v[236:239], v[172:175], v[108:111]
	v_mfma_f32_16x16x32_bf16 v[104:107], v[244:247], v[172:175], v[104:107]
	v_mfma_f32_16x16x32_bf16 v[92:95], v[236:239], v[184:187], v[92:95]
	v_mfma_f32_16x16x32_bf16 v[88:91], v[244:247], v[184:187], v[88:91]
	v_mfma_f32_16x16x32_bf16 v[76:79], v[236:239], v[192:195], v[76:79]
	v_mfma_f32_16x16x32_bf16 v[72:75], v[244:247], v[192:195], v[72:75]
	s_mov_b32 m0, s72
	s_barrier
	ds_read_b128 v[160:163], v230 offset:16384
	ds_read_b128 v[164:167], v230 offset:17408
	ds_read_b128 v[168:171], v230 offset:18432
	ds_read_b128 v[172:175], v230 offset:19456
	ds_read_b128 v[180:183], v230 offset:20480
	ds_read_b128 v[184:187], v230 offset:21504
	ds_read_b128 v[188:191], v230 offset:22528
	global_load_lds_dwordx4 v0, s[70:71]
	s_mov_b32 m0, s73
	ds_read_b128 v[192:195], v230 offset:23552
	global_load_lds_dwordx4 v2, s[70:71]
	s_barrier
	s_waitcnt lgkmcnt(0)
	s_waitcnt lgkmcnt(0)
	v_mfma_f32_16x16x32_bf16 v[68:71], v[144:147], v[160:163], v[68:71]
	v_mfma_f32_16x16x32_bf16 v[64:67], v[152:155], v[160:163], v[64:67]
	v_mfma_f32_16x16x32_bf16 v[52:55], v[144:147], v[168:171], v[52:55]
	v_mfma_f32_16x16x32_bf16 v[48:51], v[152:155], v[168:171], v[48:51]
	v_mfma_f32_16x16x32_bf16 v[36:39], v[144:147], v[180:183], v[36:39]
	v_mfma_f32_16x16x32_bf16 v[32:35], v[152:155], v[180:183], v[32:35]
	v_mfma_f32_16x16x32_bf16 v[20:23], v[144:147], v[188:191], v[20:23]
	v_mfma_f32_16x16x32_bf16 v[16:19], v[152:155], v[188:191], v[16:19]
	v_mfma_f32_16x16x32_bf16 v[68:71], v[148:151], v[164:167], v[68:71]
	v_mfma_f32_16x16x32_bf16 v[64:67], v[156:159], v[164:167], v[64:67]
	v_mfma_f32_16x16x32_bf16 v[52:55], v[148:151], v[172:175], v[52:55]
	v_mfma_f32_16x16x32_bf16 v[48:51], v[156:159], v[172:175], v[48:51]
	v_mfma_f32_16x16x32_bf16 v[36:39], v[148:151], v[184:187], v[36:39]
	v_mfma_f32_16x16x32_bf16 v[32:35], v[156:159], v[184:187], v[32:35]
	v_mfma_f32_16x16x32_bf16 v[20:23], v[148:151], v[192:195], v[20:23]
	v_mfma_f32_16x16x32_bf16 v[16:19], v[156:159], v[192:195], v[16:19]
	s_barrier
	s_add_u32 s64, s68, 0x40000
	s_addc_u32 s65, s69, 0
	s_add_i32 m0, s21, 0x14000
	s_nop 0
	global_load_lds_dwordx4 v0, s[64:65]
	s_add_i32 m0, s21, 0x16000
	s_nop 0
	global_load_lds_dwordx4 v2, s[64:65]
	s_waitcnt vmcnt(6)
	s_barrier
; #define G_STAGE(bufoff, gbase) do { _Pragma("unroll") for (int _i = 0; _i < 2; ++_i) \
;         __builtin_amdgcn_global_load_lds((const unsigned*)((const char*)(gbase) + voff[_i]), (LAS unsigned*)(lds + (bufoff) + ldsw + _i * 8192), 16, 0, 0); } while (0)
; #define G_LDA(dst, b, h) do { _Pragma("unroll") for (int m = 0; m < 4; ++m) _Pragma("unroll") for (int k = 0; k < 2; ++k) dst[m][k] = *(const LAS bf16x8*)(lds + G_SA(b, h) + aoff + m * 2048 + k * 1024); } while (0)
; #define G_LDB(dst, b, h) do { _Pragma("unroll") for (int n = 0; n < 2; ++n) _Pragma("unroll") for (int k = 0; k < 2; ++k) dst[n][k] = *(const LAS bf16x8*)(lds + G_SB(b, h) + boff + n * 2048 + k * 1024); } while (0)
; #define G_MMA(ai, bj, At, Bt) do { __builtin_amdgcn_s_setprio(1); _Pragma("unroll") for (int m = 0; m < 4; ++m) _Pragma("unroll") for (int n = 0; n < 2; ++n) _Pragma("unroll") for (int k = 0; k < 2; ++k) \
;         acc[ai][bj][m][n] = MFMA16(Bt[n][k], At[m][k], acc[ai][bj][m][n]); __builtin_amdgcn_s_setprio(0); } while (0)
; #define G_WAIT_V(n) asm volatile("s_waitcnt vmcnt(" #n ")" ::: "memory")
; #define G_WAIT_L(n) asm volatile("s_waitcnt lgkmcnt(" #n ")" ::: "memory")
; #define G_BAR __builtin_amdgcn_s_barrier()
; #define G_SCHED __builtin_amdgcn_sched_barrier(0)
; template <class Epi>
; __device__ __forceinline__ void gemm_phase(LAS unsigned char* lds, const bf16_t* Ag, const bf16_t* Btg, const int K, const int nM, const int nN, const Epi& E) {
;     ...
;         for (int t = 0; t < nt; t += 2) {
;             const bool last = (t == nt - 2);
;             const char* a1 = cA + (size_t)(t + 1) * kstep;
;             const char* a2 = last ? nA : cA + (size_t)(t + 2) * kstep; const char* b2 = last ? nB : cB + (size_t)(t + 2) * kstep;
;             const char* a3 = a2 + kstep; const char* b3 = b2 + kstep;
;     ...
;             G_WAIT_V(6); G_BAR; G_MMA(1, 1, At, B1); G_BAR;
;             G_LDB(B0, 1, 0); G_SCHED; G_LDA(At, 1, 0); G_STAGE(G_SA(0, 1), a2 + hstep);
;             G_WAIT_L(8); G_BAR; G_WAIT_L(0); G_MMA(0, 0, At, B0); G_BAR; G_SCHED;
;             G_LDB(B1, 1, 1); G_STAGE(G_SB(1, 0), b3);
;             G_BAR; G_WAIT_L(0); G_MMA(0, 1, At, B1); G_BAR;
;             G_LDA(At, 1, 1); G_STAGE(G_SA(1, 0), a3);
;             G_BAR; G_WAIT_L(0); G_MMA(1, 0, At, B0); G_BAR; G_SCHED;
;             G_STAGE(G_SB(1, 1), b3 + hstep);
	v_mfma_f32_16x16x32_bf16 v[60:63], v[232:235], v[160:163], v[60:63]
	v_mfma_f32_16x16x32_bf16 v[56:59], v[240:243], v[160:163], v[56:59]
	v_mfma_f32_16x16x32_bf16 v[44:47], v[232:235], v[168:171], v[44:47]
	v_mfma_f32_16x16x32_bf16 v[40:43], v[240:243], v[168:171], v[40:43]
	v_mfma_f32_16x16x32_bf16 v[28:31], v[232:235], v[180:183], v[28:31]
	v_mfma_f32_16x16x32_bf16 v[24:27], v[240:243], v[180:183], v[24:27]
	v_mfma_f32_16x16x32_bf16 v[12:15], v[232:235], v[188:191], v[12:15]
	v_mfma_f32_16x16x32_bf16 v[8:11], v[240:243], v[188:191], v[8:11]
	v_mfma_f32_16x16x32_bf16 v[60:63], v[236:239], v[164:167], v[60:63]
	v_mfma_f32_16x16x32_bf16 v[56:59], v[244:247], v[164:167], v[56:59]
	v_mfma_f32_16x16x32_bf16 v[44:47], v[236:239], v[172:175], v[44:47]
	v_mfma_f32_16x16x32_bf16 v[40:43], v[244:247], v[172:175], v[40:43]
	v_mfma_f32_16x16x32_bf16 v[28:31], v[236:239], v[184:187], v[28:31]
	v_mfma_f32_16x16x32_bf16 v[24:27], v[244:247], v[184:187], v[24:27]
	v_mfma_f32_16x16x32_bf16 v[12:15], v[236:239], v[192:195], v[12:15]
	v_mfma_f32_16x16x32_bf16 v[8:11], v[244:247], v[192:195], v[8:11]
	s_barrier
	ds_read_b128 v[144:147], v217 offset:32768
	ds_read_b128 v[148:151], v217 offset:33792
	ds_read_b128 v[152:155], v217 offset:34816
	ds_read_b128 v[156:159], v217 offset:35840
	s_add_u32 s64, s70, 0x40000
	s_addc_u32 s65, s71, 0
	s_mov_b32 m0, s74
	ds_read_b128 v[160:163], v230 offset:32768
	ds_read_b128 v[164:167], v230 offset:33792
	ds_read_b128 v[168:171], v230 offset:34816
	ds_read_b128 v[172:175], v230 offset:35840
	ds_read_b128 v[180:183], v230 offset:36864
	ds_read_b128 v[184:187], v230 offset:37888
	ds_read_b128 v[188:191], v230 offset:38912
	global_load_lds_dwordx4 v0, s[64:65]
	s_mov_b32 m0, s75
	ds_read_b128 v[192:195], v230 offset:39936
	global_load_lds_dwordx4 v2, s[64:65]
	s_waitcnt lgkmcnt(8)
	s_barrier
	s_waitcnt lgkmcnt(0)
	s_waitcnt lgkmcnt(0)
	v_mfma_f32_16x16x32_bf16 v[132:135], v[144:147], v[160:163], v[132:135]
	v_mfma_f32_16x16x32_bf16 v[128:131], v[152:155], v[160:163], v[128:131]
	v_mfma_f32_16x16x32_bf16 v[116:119], v[144:147], v[168:171], v[116:119]
	v_mfma_f32_16x16x32_bf16 v[112:115], v[152:155], v[168:171], v[112:115]
	v_mfma_f32_16x16x32_bf16 v[100:103], v[144:147], v[180:183], v[100:103]
	v_mfma_f32_16x16x32_bf16 v[96:99], v[152:155], v[180:183], v[96:99]
	v_mfma_f32_16x16x32_bf16 v[84:87], v[144:147], v[188:191], v[84:87]
	v_mfma_f32_16x16x32_bf16 v[80:83], v[152:155], v[188:191], v[80:83]
	v_mfma_f32_16x16x32_bf16 v[132:135], v[148:151], v[164:167], v[132:135]
	v_mfma_f32_16x16x32_bf16 v[128:131], v[156:159], v[164:167], v[128:131]
	v_mfma_f32_16x16x32_bf16 v[116:119], v[148:151], v[172:175], v[116:119]
	v_mfma_f32_16x16x32_bf16 v[112:115], v[156:159], v[172:175], v[112:115]
	v_mfma_f32_16x16x32_bf16 v[100:103], v[148:151], v[184:187], v[100:103]
	v_mfma_f32_16x16x32_bf16 v[96:99], v[156:159], v[184:187], v[96:99]
	v_mfma_f32_16x16x32_bf16 v[84:87], v[148:151], v[192:195], v[84:87]
	v_mfma_f32_16x16x32_bf16 v[80:83], v[156:159], v[192:195], v[80:83]
	s_barrier
	s_add_i32 s26, 0, 0x1c000
	s_add_i32 m0, s21, 0x18000
	ds_read_b128 v[232:235], v217 offset:49152
	ds_read_b128 v[236:239], v217 offset:50176
	ds_read_b128 v[240:243], v217 offset:51200
	ds_read_b128 v[244:247], v217 offset:52224
	s_add_u32 s98, s68, 0x80
	s_addc_u32 s99, s69, 0
	global_load_lds_dwordx4 v0, s[98:99]
	s_add_i32 m0, s21, 0x1a000
	s_nop 0
	global_load_lds_dwordx4 v2, s[98:99]
	s_barrier
	s_waitcnt lgkmcnt(0)
	s_waitcnt lgkmcnt(0)
	v_mfma_f32_16x16x32_bf16 v[124:127], v[232:235], v[160:163], v[124:127]
	v_mfma_f32_16x16x32_bf16 v[120:123], v[240:243], v[160:163], v[120:123]
	v_mfma_f32_16x16x32_bf16 v[108:111], v[232:235], v[168:171], v[108:111]
	v_mfma_f32_16x16x32_bf16 v[104:107], v[240:243], v[168:171], v[104:107]
	v_mfma_f32_16x16x32_bf16 v[92:95], v[232:235], v[180:183], v[92:95]
	v_mfma_f32_16x16x32_bf16 v[88:91], v[240:243], v[180:183], v[88:91]
	v_mfma_f32_16x16x32_bf16 v[76:79], v[232:235], v[188:191], v[76:79]
	v_mfma_f32_16x16x32_bf16 v[72:75], v[240:243], v[188:191], v[72:75]
	v_mfma_f32_16x16x32_bf16 v[124:127], v[236:239], v[164:167], v[124:127]
	v_mfma_f32_16x16x32_bf16 v[120:123], v[244:247], v[164:167], v[120:123]
	v_mfma_f32_16x16x32_bf16 v[108:111], v[236:239], v[172:175], v[108:111]
	v_mfma_f32_16x16x32_bf16 v[104:107], v[244:247], v[172:175], v[104:107]
	v_mfma_f32_16x16x32_bf16 v[92:95], v[236:239], v[184:187], v[92:95]
	v_mfma_f32_16x16x32_bf16 v[88:91], v[244:247], v[184:187], v[88:91]
	v_mfma_f32_16x16x32_bf16 v[76:79], v[236:239], v[192:195], v[76:79]
	v_mfma_f32_16x16x32_bf16 v[72:75], v[244:247], v[192:195], v[72:75]
	s_mov_b32 m0, s76
	s_barrier
	ds_read_b128 v[160:163], v230 offset:49152
	ds_read_b128 v[164:167], v230 offset:50176
	ds_read_b128 v[168:171], v230 offset:51200
	ds_read_b128 v[172:175], v230 offset:52224
	ds_read_b128 v[180:183], v230 offset:53248
	ds_read_b128 v[184:187], v230 offset:54272
	ds_read_b128 v[188:191], v230 offset:55296
	ds_read_b128 v[192:195], v230 offset:56320
	s_add_u32 s98, s70, 0x80
	s_addc_u32 s99, s71, 0
	global_load_lds_dwordx4 v0, s[98:99]
	s_mov_b32 m0, s77
	s_nop 0
	global_load_lds_dwordx4 v2, s[98:99]
	s_barrier
	s_waitcnt lgkmcnt(0)
	s_waitcnt lgkmcnt(0)
	v_mfma_f32_16x16x32_bf16 v[68:71], v[144:147], v[160:163], v[68:71]
	v_mfma_f32_16x16x32_bf16 v[64:67], v[152:155], v[160:163], v[64:67]
	v_mfma_f32_16x16x32_bf16 v[52:55], v[144:147], v[168:171], v[52:55]
	v_mfma_f32_16x16x32_bf16 v[48:51], v[152:155], v[168:171], v[48:51]
	v_mfma_f32_16x16x32_bf16 v[36:39], v[144:147], v[180:183], v[36:39]
	v_mfma_f32_16x16x32_bf16 v[32:35], v[152:155], v[180:183], v[32:35]
	v_mfma_f32_16x16x32_bf16 v[20:23], v[144:147], v[188:191], v[20:23]
	v_mfma_f32_16x16x32_bf16 v[16:19], v[152:155], v[188:191], v[16:19]
	v_mfma_f32_16x16x32_bf16 v[68:71], v[148:151], v[164:167], v[68:71]
	v_mfma_f32_16x16x32_bf16 v[64:67], v[156:159], v[164:167], v[64:67]
	v_mfma_f32_16x16x32_bf16 v[52:55], v[148:151], v[172:175], v[52:55]
	v_mfma_f32_16x16x32_bf16 v[48:51], v[156:159], v[172:175], v[48:51]
	v_mfma_f32_16x16x32_bf16 v[36:39], v[148:151], v[184:187], v[36:39]
	v_mfma_f32_16x16x32_bf16 v[32:35], v[156:159], v[184:187], v[32:35]
	v_mfma_f32_16x16x32_bf16 v[20:23], v[148:151], v[192:195], v[20:23]
	v_mfma_f32_16x16x32_bf16 v[16:19], v[156:159], v[192:195], v[16:19]
	s_barrier
	s_add_u32 s64, s68, 0x40080
	s_addc_u32 s65, s69, 0
	s_add_i32 s12, s26, s21
	s_add_i32 m0, s21, 0x1c000
	s_nop 0
	global_load_lds_dwordx4 v0, s[64:65]
	s_add_i32 m0, s21, 0x1e000
	s_nop 0
	global_load_lds_dwordx4 v2, s[64:65]
	s_add_i32 s42, s42, 2
	s_add_u32 s57, s57, 0x100
	s_addc_u32 s61, s61, 0
	s_mov_b64 s[64:65], s[66:67]
	s_cmp_gt_u32 s42, 13
	s_cbranch_scc1 .LrotX_153
	s_cmp_lg_u32 s42, 12
	s_cselect_b64 s[68:69], -1, 0
	s_add_u32 s66, s64, 0x100
	s_addc_u32 s67, s65, 0
	s_and_b64 s[68:69], s[68:69], exec
	s_cselect_b32 s71, s67, s55
	s_cselect_b32 s70, s66, s54
	s_cselect_b32 s69, s61, s14
	s_cselect_b32 s68, s57, s15
;     __device__ __forceinline__ void prep(int pm, int par, LAS unsigned char* lds) const { if (fold) prep_rowstats(stat, pm, par, lds); }
;     __device__ __forceinline__ void prep(int pm, int par, LAS unsigned char* lds) const { if (!ident) prep_rowstats(stat, pm, par, lds); }
;     __device__ __forceinline__ void prep(int pm, int par, LAS unsigned char* lds) const { prep_rowstats(stat, pm, par, lds); }
; #define G_STAGE(bufoff, gbase) do { _Pragma("unroll") for (int _i = 0; _i < 2; ++_i) \
;         __builtin_amdgcn_global_load_lds((const unsigned*)((const char*)(gbase) + voff[_i]), (LAS unsigned*)(lds + (bufoff) + ldsw + _i * 8192), 16, 0, 0); } while (0)
; #define G_MMA(ai, bj, At, Bt) do { __builtin_amdgcn_s_setprio(1); _Pragma("unroll") for (int m = 0; m < 4; ++m) _Pragma("unroll") for (int n = 0; n < 2; ++n) _Pragma("unroll") for (int k = 0; k < 2; ++k) \
;         acc[ai][bj][m][n] = MFMA16(Bt[n][k], At[m][k], acc[ai][bj][m][n]); __builtin_amdgcn_s_setprio(0); } while (0)
; #define G_WAIT_V(n) asm volatile("s_waitcnt vmcnt(" #n ")" ::: "memory")
; #define G_BAR __builtin_amdgcn_s_barrier()
; template <class Epi>
; __device__ __forceinline__ void gemm_phase(LAS unsigned char* lds, const bf16_t* Ag, const bf16_t* Btg, const int K, const int nM, const int nN, const Epi& E) {
;     ...
;         for (int t = 0; t < nt; t += 2) {
;             const bool last = (t == nt - 2);
;             const char* a1 = cA + (size_t)(t + 1) * kstep;
;             const char* a2 = last ? nA : cA + (size_t)(t + 2) * kstep; const char* b2 = last ? nB : cB + (size_t)(t + 2) * kstep;
;             const char* a3 = a2 + kstep; const char* b3 = b2 + kstep;
;             if (last && has_next && pmn != pm) E.prep(pmn, par ^ 1, lds);
;     ...
;             G_STAGE(G_SB(1, 1), b3 + hstep);
;             G_WAIT_V(6); G_BAR; G_MMA(1, 1, At, B1); G_BAR;
;         }
.LrotX_153:
	s_waitcnt vmcnt(6)
	s_barrier
	v_mfma_f32_16x16x32_bf16 v[60:63], v[232:235], v[160:163], v[60:63]
	v_mfma_f32_16x16x32_bf16 v[56:59], v[240:243], v[160:163], v[56:59]
	v_mfma_f32_16x16x32_bf16 v[44:47], v[232:235], v[168:171], v[44:47]
	v_mfma_f32_16x16x32_bf16 v[40:43], v[240:243], v[168:171], v[40:43]
	v_mfma_f32_16x16x32_bf16 v[28:31], v[232:235], v[180:183], v[28:31]
	v_mfma_f32_16x16x32_bf16 v[24:27], v[240:243], v[180:183], v[24:27]
	v_mfma_f32_16x16x32_bf16 v[12:15], v[232:235], v[188:191], v[12:15]
	v_mfma_f32_16x16x32_bf16 v[8:11], v[240:243], v[188:191], v[8:11]
	v_mfma_f32_16x16x32_bf16 v[60:63], v[236:239], v[164:167], v[60:63]
	v_mfma_f32_16x16x32_bf16 v[56:59], v[244:247], v[164:167], v[56:59]
	v_mfma_f32_16x16x32_bf16 v[44:47], v[236:239], v[172:175], v[44:47]
	v_mfma_f32_16x16x32_bf16 v[40:43], v[244:247], v[172:175], v[40:43]
	v_mfma_f32_16x16x32_bf16 v[28:31], v[236:239], v[184:187], v[28:31]
	v_mfma_f32_16x16x32_bf16 v[24:27], v[244:247], v[184:187], v[24:27]
	v_mfma_f32_16x16x32_bf16 v[12:15], v[236:239], v[192:195], v[12:15]
	v_mfma_f32_16x16x32_bf16 v[8:11], v[244:247], v[192:195], v[8:11]
	s_cmp_gt_u32 s42, 13
	s_barrier
	s_cbranch_scc1 .LBB0_157
	s_cmp_lg_u32 s42, 12
	s_cbranch_scc1 .LmainW_153

; #define G_STAGE(bufoff, gbase) do { _Pragma("unroll") for (int _i = 0; _i < 2; ++_i) \
;         __builtin_amdgcn_global_load_lds((const unsigned*)((const char*)(gbase) + voff[_i]), (LAS unsigned*)(lds + (bufoff) + ldsw + _i * 8192), 16, 0, 0); } while (0)
; #define G_LDA(dst, b, h) do { _Pragma("unroll") for (int m = 0; m < 4; ++m) _Pragma("unroll") for (int k = 0; k < 2; ++k) dst[m][k] = *(const LAS bf16x8*)(lds + G_SA(b, h) + aoff + m * 2048 + k * 1024); } while (0)
; #define G_LDB(dst, b, h) do { _Pragma("unroll") for (int n = 0; n < 2; ++n) _Pragma("unroll") for (int k = 0; k < 2; ++k) dst[n][k] = *(const LAS bf16x8*)(lds + G_SB(b, h) + boff + n * 2048 + k * 1024); } while (0)
; #define G_MMA(ai, bj, At, Bt) do { __builtin_amdgcn_s_setprio(1); _Pragma("unroll") for (int m = 0; m < 4; ++m) _Pragma("unroll") for (int n = 0; n < 2; ++n) _Pragma("unroll") for (int k = 0; k < 2; ++k) \
;         acc[ai][bj][m][n] = MFMA16(Bt[n][k], At[m][k], acc[ai][bj][m][n]); __builtin_amdgcn_s_setprio(0); } while (0)
; #define G_WAIT_V(n) asm volatile("s_waitcnt vmcnt(" #n ")" ::: "memory")
; #define G_WAIT_L(n) asm volatile("s_waitcnt lgkmcnt(" #n ")" ::: "memory")
; #define G_BAR __builtin_amdgcn_s_barrier()
; #define G_SCHED __builtin_amdgcn_sched_barrier(0)
; template <class Epi>
; __device__ __forceinline__ void gemm_phase(LAS unsigned char* lds, const bf16_t* Ag, const bf16_t* Btg, const int K, const int nM, const int nN, const Epi& E) {
;     ...
;             G_LDB(B0, 0, 0); G_SCHED; G_LDA(At, 0, 0); G_STAGE(G_SA(1, 1), a1 + hstep);
;             G_WAIT_L(8); G_BAR; G_WAIT_L(0); G_MMA(0, 0, At, B0); G_BAR; G_SCHED;
;             G_LDB(B1, 0, 1); G_STAGE(G_SB(0, 0), b2);
;             G_BAR; G_WAIT_L(0); G_MMA(0, 1, At, B1); G_BAR;
;             G_LDA(At, 0, 1); G_STAGE(G_SA(0, 0), a2);
;             G_BAR; G_WAIT_L(0); G_MMA(1, 0, At, B0); G_BAR; G_SCHED;
;             G_STAGE(G_SB(0, 1), b2 + hstep);
;             G_WAIT_V(6); G_BAR; G_MMA(1, 1, At, B1); G_BAR;
.LmainW_744:
	ds_read_b128 v[140:143], v217
	ds_read_b128 v[144:147], v217 offset:1024
	ds_read_b128 v[148:151], v217 offset:2048
	ds_read_b128 v[152:155], v217 offset:3072
	s_add_i32 m0, s66, 0xc000
	ds_read_b128 v[156:159], v174
	ds_read_b128 v[160:163], v174 offset:1024
	ds_read_b128 v[180:183], v174 offset:2048
	ds_read_b128 v[184:187], v174 offset:3072
	ds_read_b128 v[188:191], v174 offset:4096
	ds_read_b128 v[192:195], v174 offset:5120
	ds_read_b128 v[222:225], v174 offset:6144
	global_load_lds_dwordx4 v138, s[56:57]
	s_add_i32 m0, s66, 0xe000
	ds_read_b128 v[226:229], v174 offset:7168
	global_load_lds_dwordx4 v136, s[56:57]
	s_waitcnt lgkmcnt(8)
	s_barrier
	s_waitcnt lgkmcnt(0)
	s_waitcnt lgkmcnt(0)
	v_mfma_f32_16x16x32_bf16 v[132:135], v[140:143], v[156:159], v[132:135]
	v_mfma_f32_16x16x32_bf16 v[128:131], v[148:151], v[156:159], v[128:131]
	v_mfma_f32_16x16x32_bf16 v[116:119], v[140:143], v[180:183], v[116:119]
	v_mfma_f32_16x16x32_bf16 v[112:115], v[148:151], v[180:183], v[112:115]
	v_mfma_f32_16x16x32_bf16 v[100:103], v[140:143], v[188:191], v[100:103]
	v_mfma_f32_16x16x32_bf16 v[96:99], v[148:151], v[188:191], v[96:99]
	v_mfma_f32_16x16x32_bf16 v[84:87], v[140:143], v[222:225], v[84:87]
	v_mfma_f32_16x16x32_bf16 v[80:83], v[148:151], v[222:225], v[80:83]
	v_mfma_f32_16x16x32_bf16 v[132:135], v[144:147], v[160:163], v[132:135]
	v_mfma_f32_16x16x32_bf16 v[128:131], v[152:155], v[160:163], v[128:131]
	v_mfma_f32_16x16x32_bf16 v[116:119], v[144:147], v[184:187], v[116:119]
	v_mfma_f32_16x16x32_bf16 v[112:115], v[152:155], v[184:187], v[112:115]
	v_mfma_f32_16x16x32_bf16 v[100:103], v[144:147], v[192:195], v[100:103]
	v_mfma_f32_16x16x32_bf16 v[96:99], v[152:155], v[192:195], v[96:99]
	v_mfma_f32_16x16x32_bf16 v[84:87], v[144:147], v[226:229], v[84:87]
	v_mfma_f32_16x16x32_bf16 v[80:83], v[152:155], v[226:229], v[80:83]
	s_barrier
	s_add_i32 m0, s65, 0x10000
	ds_read_b128 v[230:233], v217 offset:16384
	ds_read_b128 v[234:237], v217 offset:17408
	ds_read_b128 v[238:241], v217 offset:18432
	global_load_lds_dwordx4 v0, s[60:61]
	s_add_i32 m0, s65, 0x12000
	ds_read_b128 v[242:245], v217 offset:19456
	global_load_lds_dwordx4 v2, s[60:61]
	s_barrier
	s_waitcnt lgkmcnt(0)
	s_waitcnt lgkmcnt(0)
	v_mfma_f32_16x16x32_bf16 v[124:127], v[230:233], v[156:159], v[124:127]
	v_mfma_f32_16x16x32_bf16 v[120:123], v[238:241], v[156:159], v[120:123]
	v_mfma_f32_16x16x32_bf16 v[108:111], v[230:233], v[180:183], v[108:111]
	v_mfma_f32_16x16x32_bf16 v[104:107], v[238:241], v[180:183], v[104:107]
	v_mfma_f32_16x16x32_bf16 v[92:95], v[230:233], v[188:191], v[92:95]
	v_mfma_f32_16x16x32_bf16 v[88:91], v[238:241], v[188:191], v[88:91]
	v_mfma_f32_16x16x32_bf16 v[76:79], v[230:233], v[222:225], v[76:79]
	v_mfma_f32_16x16x32_bf16 v[72:75], v[238:241], v[222:225], v[72:75]
	v_mfma_f32_16x16x32_bf16 v[124:127], v[234:237], v[160:163], v[124:127]
	v_mfma_f32_16x16x32_bf16 v[120:123], v[242:245], v[160:163], v[120:123]
	v_mfma_f32_16x16x32_bf16 v[108:111], v[234:237], v[184:187], v[108:111]
	v_mfma_f32_16x16x32_bf16 v[104:107], v[242:245], v[184:187], v[104:107]
	v_mfma_f32_16x16x32_bf16 v[92:95], v[234:237], v[192:195], v[92:95]
	v_mfma_f32_16x16x32_bf16 v[88:91], v[242:245], v[192:195], v[88:91]
	v_mfma_f32_16x16x32_bf16 v[76:79], v[234:237], v[226:229], v[76:79]
	v_mfma_f32_16x16x32_bf16 v[72:75], v[242:245], v[226:229], v[72:75]
	s_mov_b32 m0, s66
	s_barrier
	ds_read_b128 v[156:159], v174 offset:16384
	ds_read_b128 v[160:163], v174 offset:17408
	ds_read_b128 v[180:183], v174 offset:18432
	ds_read_b128 v[184:187], v174 offset:19456
	ds_read_b128 v[188:191], v174 offset:20480
	ds_read_b128 v[192:195], v174 offset:21504
	ds_read_b128 v[222:225], v174 offset:22528
	global_load_lds_dwordx4 v0, s[62:63]
	s_mov_b32 m0, s67
	ds_read_b128 v[226:229], v174 offset:23552
	global_load_lds_dwordx4 v2, s[62:63]
	s_barrier
	s_waitcnt lgkmcnt(0)
	s_waitcnt lgkmcnt(0)
	v_mfma_f32_16x16x32_bf16 v[68:71], v[140:143], v[156:159], v[68:71]
	v_mfma_f32_16x16x32_bf16 v[64:67], v[148:151], v[156:159], v[64:67]
	v_mfma_f32_16x16x32_bf16 v[52:55], v[140:143], v[180:183], v[52:55]
	v_mfma_f32_16x16x32_bf16 v[48:51], v[148:151], v[180:183], v[48:51]
	v_mfma_f32_16x16x32_bf16 v[36:39], v[140:143], v[188:191], v[36:39]
	v_mfma_f32_16x16x32_bf16 v[32:35], v[148:151], v[188:191], v[32:35]
	v_mfma_f32_16x16x32_bf16 v[20:23], v[140:143], v[222:225], v[20:23]
	v_mfma_f32_16x16x32_bf16 v[16:19], v[148:151], v[222:225], v[16:19]
	v_mfma_f32_16x16x32_bf16 v[68:71], v[144:147], v[160:163], v[68:71]
	v_mfma_f32_16x16x32_bf16 v[64:67], v[152:155], v[160:163], v[64:67]
	v_mfma_f32_16x16x32_bf16 v[52:55], v[144:147], v[184:187], v[52:55]
	v_mfma_f32_16x16x32_bf16 v[48:51], v[152:155], v[184:187], v[48:51]
	v_mfma_f32_16x16x32_bf16 v[36:39], v[144:147], v[192:195], v[36:39]
	v_mfma_f32_16x16x32_bf16 v[32:35], v[152:155], v[192:195], v[32:35]
	v_mfma_f32_16x16x32_bf16 v[20:23], v[144:147], v[226:229], v[20:23]
	v_mfma_f32_16x16x32_bf16 v[16:19], v[152:155], v[226:229], v[16:19]
	s_barrier
	s_add_u32 s56, s60, 0x100000
	s_addc_u32 s57, s61, 0
	s_add_i32 m0, s65, 0x14000
	s_nop 0
	global_load_lds_dwordx4 v0, s[56:57]
	s_add_i32 m0, s65, 0x16000
	s_nop 0
	global_load_lds_dwordx4 v2, s[56:57]
	s_waitcnt vmcnt(6)
	s_barrier
; #define G_STAGE(bufoff, gbase) do { _Pragma("unroll") for (int _i = 0; _i < 2; ++_i) \
;         __builtin_amdgcn_global_load_lds((const unsigned*)((const char*)(gbase) + voff[_i]), (LAS unsigned*)(lds + (bufoff) + ldsw + _i * 8192), 16, 0, 0); } while (0)
; #define G_LDA(dst, b, h) do { _Pragma("unroll") for (int m = 0; m < 4; ++m) _Pragma("unroll") for (int k = 0; k < 2; ++k) dst[m][k] = *(const LAS bf16x8*)(lds + G_SA(b, h) + aoff + m * 2048 + k * 1024); } while (0)
; #define G_LDB(dst, b, h) do { _Pragma("unroll") for (int n = 0; n < 2; ++n) _Pragma("unroll") for (int k = 0; k < 2; ++k) dst[n][k] = *(const LAS bf16x8*)(lds + G_SB(b, h) + boff + n * 2048 + k * 1024); } while (0)
; #define G_MMA(ai, bj, At, Bt) do { __builtin_amdgcn_s_setprio(1); _Pragma("unroll") for (int m = 0; m < 4; ++m) _Pragma("unroll") for (int n = 0; n < 2; ++n) _Pragma("unroll") for (int k = 0; k < 2; ++k) \
;         acc[ai][bj][m][n] = MFMA16(Bt[n][k], At[m][k], acc[ai][bj][m][n]); __builtin_amdgcn_s_setprio(0); } while (0)
; #define G_WAIT_V(n) asm volatile("s_waitcnt vmcnt(" #n ")" ::: "memory")
; #define G_WAIT_L(n) asm volatile("s_waitcnt lgkmcnt(" #n ")" ::: "memory")
; #define G_BAR __builtin_amdgcn_s_barrier()
; #define G_SCHED __builtin_amdgcn_sched_barrier(0)
; template <class Epi>
; __device__ __forceinline__ void gemm_phase(LAS unsigned char* lds, const bf16_t* Ag, const bf16_t* Btg, const int K, const int nM, const int nN, const Epi& E) {
;     ...
;         for (int t = 0; t < nt; t += 2) {
;             const bool last = (t == nt - 2);
;             const char* a1 = cA + (size_t)(t + 1) * kstep;
;             const char* a2 = last ? nA : cA + (size_t)(t + 2) * kstep; const char* b2 = last ? nB : cB + (size_t)(t + 2) * kstep;
;             const char* a3 = a2 + kstep; const char* b3 = b2 + kstep;
;     ...
;             G_WAIT_V(6); G_BAR; G_MMA(1, 1, At, B1); G_BAR;
;             G_LDB(B0, 1, 0); G_SCHED; G_LDA(At, 1, 0); G_STAGE(G_SA(0, 1), a2 + hstep);
;             G_WAIT_L(8); G_BAR; G_WAIT_L(0); G_MMA(0, 0, At, B0); G_BAR; G_SCHED;
;             G_LDB(B1, 1, 1); G_STAGE(G_SB(1, 0), b3);
;             G_BAR; G_WAIT_L(0); G_MMA(0, 1, At, B1); G_BAR;
;             G_LDA(At, 1, 1); G_STAGE(G_SA(1, 0), a3);
;             G_BAR; G_WAIT_L(0); G_MMA(1, 0, At, B0); G_BAR; G_SCHED;
;             G_STAGE(G_SB(1, 1), b3 + hstep);
	v_mfma_f32_16x16x32_bf16 v[60:63], v[230:233], v[156:159], v[60:63]
	v_mfma_f32_16x16x32_bf16 v[56:59], v[238:241], v[156:159], v[56:59]
	v_mfma_f32_16x16x32_bf16 v[44:47], v[230:233], v[180:183], v[44:47]
	v_mfma_f32_16x16x32_bf16 v[40:43], v[238:241], v[180:183], v[40:43]
	v_mfma_f32_16x16x32_bf16 v[28:31], v[230:233], v[188:191], v[28:31]
	v_mfma_f32_16x16x32_bf16 v[24:27], v[238:241], v[188:191], v[24:27]
	v_mfma_f32_16x16x32_bf16 v[12:15], v[230:233], v[222:225], v[12:15]
	v_mfma_f32_16x16x32_bf16 v[8:11], v[238:241], v[222:225], v[8:11]
	v_mfma_f32_16x16x32_bf16 v[60:63], v[234:237], v[160:163], v[60:63]
	v_mfma_f32_16x16x32_bf16 v[56:59], v[242:245], v[160:163], v[56:59]
	v_mfma_f32_16x16x32_bf16 v[44:47], v[234:237], v[184:187], v[44:47]
	v_mfma_f32_16x16x32_bf16 v[40:43], v[242:245], v[184:187], v[40:43]
	v_mfma_f32_16x16x32_bf16 v[28:31], v[234:237], v[192:195], v[28:31]
	v_mfma_f32_16x16x32_bf16 v[24:27], v[242:245], v[192:195], v[24:27]
	v_mfma_f32_16x16x32_bf16 v[12:15], v[234:237], v[226:229], v[12:15]
	v_mfma_f32_16x16x32_bf16 v[8:11], v[242:245], v[226:229], v[8:11]
	s_barrier
	ds_read_b128 v[140:143], v217 offset:32768
	ds_read_b128 v[144:147], v217 offset:33792
	ds_read_b128 v[148:151], v217 offset:34816
	ds_read_b128 v[152:155], v217 offset:35840
	s_add_u32 s56, s62, 0x100000
	s_addc_u32 s57, s63, 0
	s_mov_b32 m0, s68
	ds_read_b128 v[156:159], v174 offset:32768
	ds_read_b128 v[160:163], v174 offset:33792
	ds_read_b128 v[180:183], v174 offset:34816
	ds_read_b128 v[184:187], v174 offset:35840
	ds_read_b128 v[188:191], v174 offset:36864
	ds_read_b128 v[192:195], v174 offset:37888
	ds_read_b128 v[222:225], v174 offset:38912
	global_load_lds_dwordx4 v0, s[56:57]
	s_mov_b32 m0, s69
	ds_read_b128 v[226:229], v174 offset:39936
	global_load_lds_dwordx4 v2, s[56:57]
	s_waitcnt lgkmcnt(8)
	s_barrier
	s_waitcnt lgkmcnt(0)
	s_waitcnt lgkmcnt(0)
	v_mfma_f32_16x16x32_bf16 v[132:135], v[140:143], v[156:159], v[132:135]
	v_mfma_f32_16x16x32_bf16 v[128:131], v[148:151], v[156:159], v[128:131]
	v_mfma_f32_16x16x32_bf16 v[116:119], v[140:143], v[180:183], v[116:119]
	v_mfma_f32_16x16x32_bf16 v[112:115], v[148:151], v[180:183], v[112:115]
	v_mfma_f32_16x16x32_bf16 v[100:103], v[140:143], v[188:191], v[100:103]
	v_mfma_f32_16x16x32_bf16 v[96:99], v[148:151], v[188:191], v[96:99]
	v_mfma_f32_16x16x32_bf16 v[84:87], v[140:143], v[222:225], v[84:87]
	v_mfma_f32_16x16x32_bf16 v[80:83], v[148:151], v[222:225], v[80:83]
	v_mfma_f32_16x16x32_bf16 v[132:135], v[144:147], v[160:163], v[132:135]
	v_mfma_f32_16x16x32_bf16 v[128:131], v[152:155], v[160:163], v[128:131]
	v_mfma_f32_16x16x32_bf16 v[116:119], v[144:147], v[184:187], v[116:119]
	v_mfma_f32_16x16x32_bf16 v[112:115], v[152:155], v[184:187], v[112:115]
	v_mfma_f32_16x16x32_bf16 v[100:103], v[144:147], v[192:195], v[100:103]
	v_mfma_f32_16x16x32_bf16 v[96:99], v[152:155], v[192:195], v[96:99]
	v_mfma_f32_16x16x32_bf16 v[84:87], v[144:147], v[226:229], v[84:87]
	v_mfma_f32_16x16x32_bf16 v[80:83], v[152:155], v[226:229], v[80:83]
	s_barrier
	s_add_i32 s26, 0, 0x1c000
	s_add_i32 m0, s65, 0x18000
	ds_read_b128 v[230:233], v217 offset:49152
	ds_read_b128 v[234:237], v217 offset:50176
	ds_read_b128 v[238:241], v217 offset:51200
	ds_read_b128 v[242:245], v217 offset:52224
	s_add_u32 s98, s60, 0x80
	s_addc_u32 s99, s61, 0
	global_load_lds_dwordx4 v0, s[98:99]
	s_add_i32 m0, s65, 0x1a000
	s_nop 0
	global_load_lds_dwordx4 v2, s[98:99]
	s_barrier
	s_waitcnt lgkmcnt(0)
	s_waitcnt lgkmcnt(0)
	v_mfma_f32_16x16x32_bf16 v[124:127], v[230:233], v[156:159], v[124:127]
	v_mfma_f32_16x16x32_bf16 v[120:123], v[238:241], v[156:159], v[120:123]
	v_mfma_f32_16x16x32_bf16 v[108:111], v[230:233], v[180:183], v[108:111]
	v_mfma_f32_16x16x32_bf16 v[104:107], v[238:241], v[180:183], v[104:107]
	v_mfma_f32_16x16x32_bf16 v[92:95], v[230:233], v[188:191], v[92:95]
	v_mfma_f32_16x16x32_bf16 v[88:91], v[238:241], v[188:191], v[88:91]
	v_mfma_f32_16x16x32_bf16 v[76:79], v[230:233], v[222:225], v[76:79]
	v_mfma_f32_16x16x32_bf16 v[72:75], v[238:241], v[222:225], v[72:75]
	v_mfma_f32_16x16x32_bf16 v[124:127], v[234:237], v[160:163], v[124:127]
	v_mfma_f32_16x16x32_bf16 v[120:123], v[242:245], v[160:163], v[120:123]
	v_mfma_f32_16x16x32_bf16 v[108:111], v[234:237], v[184:187], v[108:111]
	v_mfma_f32_16x16x32_bf16 v[104:107], v[242:245], v[184:187], v[104:107]
	v_mfma_f32_16x16x32_bf16 v[92:95], v[234:237], v[192:195], v[92:95]
	v_mfma_f32_16x16x32_bf16 v[88:91], v[242:245], v[192:195], v[88:91]
	v_mfma_f32_16x16x32_bf16 v[76:79], v[234:237], v[226:229], v[76:79]
	v_mfma_f32_16x16x32_bf16 v[72:75], v[242:245], v[226:229], v[72:75]
	s_mov_b32 m0, s70
	s_barrier
	ds_read_b128 v[156:159], v174 offset:49152
	ds_read_b128 v[160:163], v174 offset:50176
	ds_read_b128 v[180:183], v174 offset:51200
	ds_read_b128 v[184:187], v174 offset:52224
	ds_read_b128 v[188:191], v174 offset:53248
	ds_read_b128 v[192:195], v174 offset:54272
	ds_read_b128 v[222:225], v174 offset:55296
	ds_read_b128 v[226:229], v174 offset:56320
	s_add_u32 s98, s62, 0x80
	s_addc_u32 s99, s63, 0
	global_load_lds_dwordx4 v0, s[98:99]
	s_mov_b32 m0, s71
	s_nop 0
	global_load_lds_dwordx4 v2, s[98:99]
	s_barrier
	s_waitcnt lgkmcnt(0)
	s_waitcnt lgkmcnt(0)
	v_mfma_f32_16x16x32_bf16 v[68:71], v[140:143], v[156:159], v[68:71]
	v_mfma_f32_16x16x32_bf16 v[64:67], v[148:151], v[156:159], v[64:67]
	v_mfma_f32_16x16x32_bf16 v[52:55], v[140:143], v[180:183], v[52:55]
	v_mfma_f32_16x16x32_bf16 v[48:51], v[148:151], v[180:183], v[48:51]
	v_mfma_f32_16x16x32_bf16 v[36:39], v[140:143], v[188:191], v[36:39]
	v_mfma_f32_16x16x32_bf16 v[32:35], v[148:151], v[188:191], v[32:35]
	v_mfma_f32_16x16x32_bf16 v[20:23], v[140:143], v[222:225], v[20:23]
	v_mfma_f32_16x16x32_bf16 v[16:19], v[148:151], v[222:225], v[16:19]
	v_mfma_f32_16x16x32_bf16 v[68:71], v[144:147], v[160:163], v[68:71]
	v_mfma_f32_16x16x32_bf16 v[64:67], v[152:155], v[160:163], v[64:67]
	v_mfma_f32_16x16x32_bf16 v[52:55], v[144:147], v[184:187], v[52:55]
	v_mfma_f32_16x16x32_bf16 v[48:51], v[152:155], v[184:187], v[48:51]
	v_mfma_f32_16x16x32_bf16 v[36:39], v[144:147], v[192:195], v[36:39]
	v_mfma_f32_16x16x32_bf16 v[32:35], v[152:155], v[192:195], v[32:35]
	v_mfma_f32_16x16x32_bf16 v[20:23], v[144:147], v[226:229], v[20:23]
	v_mfma_f32_16x16x32_bf16 v[16:19], v[152:155], v[226:229], v[16:19]
	s_barrier
	s_add_u32 s56, s60, 0x100080
	s_addc_u32 s57, s61, 0
	s_add_i32 s12, s26, s65
	s_add_i32 m0, s65, 0x1c000
	s_nop 0
	global_load_lds_dwordx4 v0, s[56:57]
	s_add_i32 m0, s65, 0x1e000
	s_nop 0
	global_load_lds_dwordx4 v2, s[56:57]
	s_add_i32 s79, s79, 2
	s_add_u32 s77, s77, 0x100
	s_addc_u32 s78, s78, 0
	s_mov_b64 s[56:57], s[58:59]
	s_cmp_gt_u32 s79, 61
	s_cbranch_scc1 .LrotX_744
	s_cmp_lg_u32 s79, 60
	s_cselect_b64 s[60:61], -1, 0
	s_add_u32 s58, s56, 0x100
	s_addc_u32 s59, s57, 0
	s_and_b64 s[60:61], s[60:61], exec
	s_cselect_b32 s63, s59, s47
	s_cselect_b32 s62, s58, s46
	s_cselect_b32 s61, s78, s15
	s_cselect_b32 s60, s77, s49
;     __device__ __forceinline__ void prep(int pm, int par, LAS unsigned char* lds) const { if (fold) prep_rowstats(stat, pm, par, lds); }
;     __device__ __forceinline__ void prep(int pm, int par, LAS unsigned char* lds) const { if (!ident) prep_rowstats(stat, pm, par, lds); }
;     __device__ __forceinline__ void prep(int pm, int par, LAS unsigned char* lds) const { prep_rowstats(stat, pm, par, lds); }
; #define G_STAGE(bufoff, gbase) do { _Pragma("unroll") for (int _i = 0; _i < 2; ++_i) \
;         __builtin_amdgcn_global_load_lds((const unsigned*)((const char*)(gbase) + voff[_i]), (LAS unsigned*)(lds + (bufoff) + ldsw + _i * 8192), 16, 0, 0); } while (0)
; #define G_MMA(ai, bj, At, Bt) do { __builtin_amdgcn_s_setprio(1); _Pragma("unroll") for (int m = 0; m < 4; ++m) _Pragma("unroll") for (int n = 0; n < 2; ++n) _Pragma("unroll") for (int k = 0; k < 2; ++k) \
;         acc[ai][bj][m][n] = MFMA16(Bt[n][k], At[m][k], acc[ai][bj][m][n]); __builtin_amdgcn_s_setprio(0); } while (0)
; #define G_WAIT_V(n) asm volatile("s_waitcnt vmcnt(" #n ")" ::: "memory")
; #define G_BAR __builtin_amdgcn_s_barrier()
; template <class Epi>
; __device__ __forceinline__ void gemm_phase(LAS unsigned char* lds, const bf16_t* Ag, const bf16_t* Btg, const int K, const int nM, const int nN, const Epi& E) {
;     ...
;         for (int t = 0; t < nt; t += 2) {
;             const bool last = (t == nt - 2);
;             const char* a1 = cA + (size_t)(t + 1) * kstep;
;             const char* a2 = last ? nA : cA + (size_t)(t + 2) * kstep; const char* b2 = last ? nB : cB + (size_t)(t + 2) * kstep;
;             const char* a3 = a2 + kstep; const char* b3 = b2 + kstep;
;             if (last && has_next && pmn != pm) E.prep(pmn, par ^ 1, lds);
;     ...
;             G_STAGE(G_SB(1, 1), b3 + hstep);
;             G_WAIT_V(6); G_BAR; G_MMA(1, 1, At, B1); G_BAR;
;         }
.LrotX_744:
	s_waitcnt vmcnt(6)
	s_barrier
	v_mfma_f32_16x16x32_bf16 v[60:63], v[230:233], v[156:159], v[60:63]
	v_mfma_f32_16x16x32_bf16 v[56:59], v[238:241], v[156:159], v[56:59]
	v_mfma_f32_16x16x32_bf16 v[44:47], v[230:233], v[180:183], v[44:47]
	v_mfma_f32_16x16x32_bf16 v[40:43], v[238:241], v[180:183], v[40:43]
	v_mfma_f32_16x16x32_bf16 v[28:31], v[230:233], v[188:191], v[28:31]
	v_mfma_f32_16x16x32_bf16 v[24:27], v[238:241], v[188:191], v[24:27]
	v_mfma_f32_16x16x32_bf16 v[12:15], v[230:233], v[222:225], v[12:15]
	v_mfma_f32_16x16x32_bf16 v[8:11], v[238:241], v[222:225], v[8:11]
	v_mfma_f32_16x16x32_bf16 v[60:63], v[234:237], v[160:163], v[60:63]
	v_mfma_f32_16x16x32_bf16 v[56:59], v[242:245], v[160:163], v[56:59]
	v_mfma_f32_16x16x32_bf16 v[44:47], v[234:237], v[184:187], v[44:47]
	v_mfma_f32_16x16x32_bf16 v[40:43], v[242:245], v[184:187], v[40:43]
	v_mfma_f32_16x16x32_bf16 v[28:31], v[234:237], v[192:195], v[28:31]
	v_mfma_f32_16x16x32_bf16 v[24:27], v[242:245], v[192:195], v[24:27]
	v_mfma_f32_16x16x32_bf16 v[12:15], v[234:237], v[226:229], v[12:15]
	v_mfma_f32_16x16x32_bf16 v[8:11], v[242:245], v[226:229], v[8:11]
	s_cmp_gt_u32 s79, 61
	s_barrier
	s_cbranch_scc1 .LBB0_748
	s_cmp_lg_u32 s79, 60
	s_cbranch_scc1 .LmainW_744

; #define G_STAGE(bufoff, gbase) do { _Pragma("unroll") for (int _i = 0; _i < 2; ++_i) \
;         __builtin_amdgcn_global_load_lds((const unsigned*)((const char*)(gbase) + voff[_i]), (LAS unsigned*)(lds + (bufoff) + ldsw + _i * 8192), 16, 0, 0); } while (0)
; #define G_LDA(dst, b, h) do { _Pragma("unroll") for (int m = 0; m < 4; ++m) _Pragma("unroll") for (int k = 0; k < 2; ++k) dst[m][k] = *(const LAS bf16x8*)(lds + G_SA(b, h) + aoff + m * 2048 + k * 1024); } while (0)
; #define G_LDB(dst, b, h) do { _Pragma("unroll") for (int n = 0; n < 2; ++n) _Pragma("unroll") for (int k = 0; k < 2; ++k) dst[n][k] = *(const LAS bf16x8*)(lds + G_SB(b, h) + boff + n * 2048 + k * 1024); } while (0)
; #define G_MMA(ai, bj, At, Bt) do { __builtin_amdgcn_s_setprio(1); _Pragma("unroll") for (int m = 0; m < 4; ++m) _Pragma("unroll") for (int n = 0; n < 2; ++n) _Pragma("unroll") for (int k = 0; k < 2; ++k) \
;         acc[ai][bj][m][n] = MFMA16(Bt[n][k], At[m][k], acc[ai][bj][m][n]); __builtin_amdgcn_s_setprio(0); } while (0)
; #define G_WAIT_V(n) asm volatile("s_waitcnt vmcnt(" #n ")" ::: "memory")
; #define G_WAIT_L(n) asm volatile("s_waitcnt lgkmcnt(" #n ")" ::: "memory")
; #define G_BAR __builtin_amdgcn_s_barrier()
; #define G_SCHED __builtin_amdgcn_sched_barrier(0)
; template <class Epi>
; __device__ __forceinline__ void gemm_phase(LAS unsigned char* lds, const bf16_t* Ag, const bf16_t* Btg, const int K, const int nM, const int nN, const Epi& E) {
;     ...
;             G_LDB(B0, 0, 0); G_SCHED; G_LDA(At, 0, 0); G_STAGE(G_SA(1, 1), a1 + hstep);
;             G_WAIT_L(8); G_BAR; G_WAIT_L(0); G_MMA(0, 0, At, B0); G_BAR; G_SCHED;
;             G_LDB(B1, 0, 1); G_STAGE(G_SB(0, 0), b2);
;             G_BAR; G_WAIT_L(0); G_MMA(0, 1, At, B1); G_BAR;
;             G_LDA(At, 0, 1); G_STAGE(G_SA(0, 0), a2);
;             G_BAR; G_WAIT_L(0); G_MMA(1, 0, At, B0); G_BAR; G_SCHED;
;             G_STAGE(G_SB(0, 1), b2 + hstep);
;             G_WAIT_V(6); G_BAR; G_MMA(1, 1, At, B1); G_BAR;
.LmainW_848:
	ds_read_b128 v[130:133], v217
	ds_read_b128 v[134:137], v217 offset:1024
	ds_read_b128 v[144:147], v217 offset:2048
	ds_read_b128 v[148:151], v217 offset:3072
	s_add_i32 m0, s60, 0xc000
	ds_read_b128 v[156:159], v222
	ds_read_b128 v[160:163], v222 offset:1024
	ds_read_b128 v[164:167], v222 offset:2048
	ds_read_b128 v[180:183], v222 offset:3072
	ds_read_b128 v[184:187], v222 offset:4096
	ds_read_b128 v[224:227], v222 offset:5120
	ds_read_b128 v[228:231], v222 offset:6144
	global_load_lds_dwordx4 v170, s[50:51]
	s_add_i32 m0, s60, 0xe000
	ds_read_b128 v[232:235], v222 offset:7168
	global_load_lds_dwordx4 v168, s[50:51]
	s_waitcnt lgkmcnt(8)
	s_barrier
	s_waitcnt lgkmcnt(0)
	s_waitcnt lgkmcnt(0)
	v_mfma_f32_16x16x32_bf16 v[152:155], v[130:133], v[156:159], v[152:155]
	v_mfma_f32_16x16x32_bf16 v[138:141], v[144:147], v[156:159], v[140:143]
	v_mfma_f32_16x16x32_bf16 v[116:119], v[130:133], v[164:167], v[116:119]
	v_mfma_f32_16x16x32_bf16 v[112:115], v[144:147], v[164:167], v[112:115]
	v_mfma_f32_16x16x32_bf16 v[100:103], v[130:133], v[184:187], v[100:103]
	v_mfma_f32_16x16x32_bf16 v[96:99], v[144:147], v[184:187], v[96:99]
	v_mfma_f32_16x16x32_bf16 v[84:87], v[130:133], v[228:231], v[84:87]
	v_mfma_f32_16x16x32_bf16 v[80:83], v[144:147], v[228:231], v[80:83]
	v_mfma_f32_16x16x32_bf16 v[152:155], v[134:137], v[160:163], v[152:155]
	v_mfma_f32_16x16x32_bf16 v[138:141], v[148:151], v[160:163], v[138:141]
	v_mfma_f32_16x16x32_bf16 v[116:119], v[134:137], v[180:183], v[116:119]
	v_mfma_f32_16x16x32_bf16 v[112:115], v[148:151], v[180:183], v[112:115]
	v_mfma_f32_16x16x32_bf16 v[100:103], v[134:137], v[224:227], v[100:103]
	v_mfma_f32_16x16x32_bf16 v[96:99], v[148:151], v[224:227], v[96:99]
	v_mfma_f32_16x16x32_bf16 v[84:87], v[134:137], v[232:235], v[84:87]
	v_mfma_f32_16x16x32_bf16 v[80:83], v[148:151], v[232:235], v[80:83]
	s_barrier
	s_add_i32 s73, 0, 0x14000
	s_add_i32 m0, s59, 0x10000
	ds_read_b128 v[236:239], v217 offset:16384
	ds_read_b128 v[240:243], v217 offset:17408
	ds_read_b128 v[244:247], v217 offset:18432
	global_load_lds_dwordx4 v0, s[52:53]
	s_add_i32 m0, s59, 0x12000
	ds_read_b128 v[248:251], v217 offset:19456
	global_load_lds_dwordx4 v2, s[52:53]
	s_barrier
	s_waitcnt lgkmcnt(0)
	s_waitcnt lgkmcnt(0)
	v_mfma_f32_16x16x32_bf16 v[124:127], v[236:239], v[156:159], v[124:127]
	v_mfma_f32_16x16x32_bf16 v[120:123], v[244:247], v[156:159], v[120:123]
	v_mfma_f32_16x16x32_bf16 v[108:111], v[236:239], v[164:167], v[108:111]
	v_mfma_f32_16x16x32_bf16 v[104:107], v[244:247], v[164:167], v[104:107]
	v_mfma_f32_16x16x32_bf16 v[92:95], v[236:239], v[184:187], v[92:95]
	v_mfma_f32_16x16x32_bf16 v[88:91], v[244:247], v[184:187], v[88:91]
	v_mfma_f32_16x16x32_bf16 v[76:79], v[236:239], v[228:231], v[76:79]
	v_mfma_f32_16x16x32_bf16 v[72:75], v[244:247], v[228:231], v[72:75]
	v_mfma_f32_16x16x32_bf16 v[124:127], v[240:243], v[160:163], v[124:127]
	v_mfma_f32_16x16x32_bf16 v[120:123], v[248:251], v[160:163], v[120:123]
	v_mfma_f32_16x16x32_bf16 v[108:111], v[240:243], v[180:183], v[108:111]
	v_mfma_f32_16x16x32_bf16 v[104:107], v[248:251], v[180:183], v[104:107]
	v_mfma_f32_16x16x32_bf16 v[92:95], v[240:243], v[224:227], v[92:95]
	v_mfma_f32_16x16x32_bf16 v[88:91], v[248:251], v[224:227], v[88:91]
	v_mfma_f32_16x16x32_bf16 v[76:79], v[240:243], v[232:235], v[76:79]
	v_mfma_f32_16x16x32_bf16 v[72:75], v[248:251], v[232:235], v[72:75]
	s_mov_b32 m0, s60
	s_add_u32 s76, s54, 0x80
	s_addc_u32 s77, s55, 0
	s_barrier
	ds_read_b128 v[156:159], v222 offset:16384
	ds_read_b128 v[160:163], v222 offset:17408
	ds_read_b128 v[164:167], v222 offset:18432
	ds_read_b128 v[180:183], v222 offset:19456
	ds_read_b128 v[184:187], v222 offset:20480
	ds_read_b128 v[224:227], v222 offset:21504
	ds_read_b128 v[228:231], v222 offset:22528
	ds_read_b128 v[232:235], v222 offset:23552
	global_load_lds_dwordx4 v0, s[54:55]
	s_add_u32 s76, s54, 0x80
	s_mov_b32 m0, s61
	s_addc_u32 s77, s55, 0
	global_load_lds_dwordx4 v2, s[54:55]
	s_barrier
	s_waitcnt lgkmcnt(0)
	s_waitcnt lgkmcnt(0)
	v_mfma_f32_16x16x32_bf16 v[60:63], v[130:133], v[156:159], v[60:63]
	v_mfma_f32_16x16x32_bf16 v[56:59], v[144:147], v[156:159], v[56:59]
	v_mfma_f32_16x16x32_bf16 v[44:47], v[130:133], v[164:167], v[44:47]
	v_mfma_f32_16x16x32_bf16 v[40:43], v[144:147], v[164:167], v[40:43]
	v_mfma_f32_16x16x32_bf16 v[28:31], v[130:133], v[184:187], v[28:31]
	v_mfma_f32_16x16x32_bf16 v[24:27], v[144:147], v[184:187], v[24:27]
	v_mfma_f32_16x16x32_bf16 v[12:15], v[130:133], v[228:231], v[12:15]
	v_mfma_f32_16x16x32_bf16 v[8:11], v[144:147], v[228:231], v[8:11]
	v_mfma_f32_16x16x32_bf16 v[60:63], v[134:137], v[160:163], v[60:63]
	v_mfma_f32_16x16x32_bf16 v[56:59], v[148:151], v[160:163], v[56:59]
	v_mfma_f32_16x16x32_bf16 v[44:47], v[134:137], v[180:183], v[44:47]
	v_mfma_f32_16x16x32_bf16 v[40:43], v[148:151], v[180:183], v[40:43]
	v_mfma_f32_16x16x32_bf16 v[28:31], v[134:137], v[224:227], v[28:31]
	v_mfma_f32_16x16x32_bf16 v[24:27], v[148:151], v[224:227], v[24:27]
	v_mfma_f32_16x16x32_bf16 v[12:15], v[134:137], v[232:235], v[12:15]
	v_mfma_f32_16x16x32_bf16 v[8:11], v[148:151], v[232:235], v[8:11]
	s_barrier
	s_add_u32 s74, s52, 0x40000
	s_addc_u32 s75, s53, 0
	s_add_i32 m0, s59, 0x14000
	s_nop 0
	global_load_lds_dwordx4 v0, s[74:75]
	s_add_i32 m0, s59, 0x16000
	s_nop 0
	global_load_lds_dwordx4 v2, s[74:75]
	s_waitcnt vmcnt(6)
	s_barrier
; #define G_STAGE(bufoff, gbase) do { _Pragma("unroll") for (int _i = 0; _i < 2; ++_i) \
;         __builtin_amdgcn_global_load_lds((const unsigned*)((const char*)(gbase) + voff[_i]), (LAS unsigned*)(lds + (bufoff) + ldsw + _i * 8192), 16, 0, 0); } while (0)
; #define G_LDA(dst, b, h) do { _Pragma("unroll") for (int m = 0; m < 4; ++m) _Pragma("unroll") for (int k = 0; k < 2; ++k) dst[m][k] = *(const LAS bf16x8*)(lds + G_SA(b, h) + aoff + m * 2048 + k * 1024); } while (0)
; #define G_LDB(dst, b, h) do { _Pragma("unroll") for (int n = 0; n < 2; ++n) _Pragma("unroll") for (int k = 0; k < 2; ++k) dst[n][k] = *(const LAS bf16x8*)(lds + G_SB(b, h) + boff + n * 2048 + k * 1024); } while (0)
; #define G_MMA(ai, bj, At, Bt) do { __builtin_amdgcn_s_setprio(1); _Pragma("unroll") for (int m = 0; m < 4; ++m) _Pragma("unroll") for (int n = 0; n < 2; ++n) _Pragma("unroll") for (int k = 0; k < 2; ++k) \
;         acc[ai][bj][m][n] = MFMA16(Bt[n][k], At[m][k], acc[ai][bj][m][n]); __builtin_amdgcn_s_setprio(0); } while (0)
; #define G_WAIT_V(n) asm volatile("s_waitcnt vmcnt(" #n ")" ::: "memory")
; #define G_WAIT_L(n) asm volatile("s_waitcnt lgkmcnt(" #n ")" ::: "memory")
; #define G_BAR __builtin_amdgcn_s_barrier()
; #define G_SCHED __builtin_amdgcn_sched_barrier(0)
; template <class Epi>
; __device__ __forceinline__ void gemm_phase(LAS unsigned char* lds, const bf16_t* Ag, const bf16_t* Btg, const int K, const int nM, const int nN, const Epi& E) {
;     ...
;         for (int t = 0; t < nt; t += 2) {
;             const bool last = (t == nt - 2);
;             const char* a1 = cA + (size_t)(t + 1) * kstep;
;             const char* a2 = last ? nA : cA + (size_t)(t + 2) * kstep; const char* b2 = last ? nB : cB + (size_t)(t + 2) * kstep;
;             const char* a3 = a2 + kstep; const char* b3 = b2 + kstep;
;     ...
;             G_WAIT_V(6); G_BAR; G_MMA(1, 1, At, B1); G_BAR;
;             G_LDB(B0, 1, 0); G_SCHED; G_LDA(At, 1, 0); G_STAGE(G_SA(0, 1), a2 + hstep);
;             G_WAIT_L(8); G_BAR; G_WAIT_L(0); G_MMA(0, 0, At, B0); G_BAR; G_SCHED;
;             G_LDB(B1, 1, 1); G_STAGE(G_SB(1, 0), b3);
;             G_BAR; G_WAIT_L(0); G_MMA(0, 1, At, B1); G_BAR;
;             G_LDA(At, 1, 1); G_STAGE(G_SA(1, 0), a3);
;             G_BAR; G_WAIT_L(0); G_MMA(1, 0, At, B0); G_BAR; G_SCHED;
;             G_STAGE(G_SB(1, 1), b3 + hstep);
	v_mfma_f32_16x16x32_bf16 v[68:71], v[236:239], v[156:159], v[68:71]
	v_mfma_f32_16x16x32_bf16 v[64:67], v[244:247], v[156:159], v[64:67]
	v_mfma_f32_16x16x32_bf16 v[52:55], v[236:239], v[164:167], v[52:55]
	v_mfma_f32_16x16x32_bf16 v[48:51], v[244:247], v[164:167], v[48:51]
	v_mfma_f32_16x16x32_bf16 v[36:39], v[236:239], v[184:187], v[36:39]
	v_mfma_f32_16x16x32_bf16 v[32:35], v[244:247], v[184:187], v[32:35]
	v_mfma_f32_16x16x32_bf16 v[20:23], v[236:239], v[228:231], v[20:23]
	v_mfma_f32_16x16x32_bf16 v[16:19], v[244:247], v[228:231], v[16:19]
	v_mfma_f32_16x16x32_bf16 v[68:71], v[240:243], v[160:163], v[68:71]
	v_mfma_f32_16x16x32_bf16 v[64:67], v[248:251], v[160:163], v[64:67]
	v_mfma_f32_16x16x32_bf16 v[52:55], v[240:243], v[180:183], v[52:55]
	v_mfma_f32_16x16x32_bf16 v[48:51], v[248:251], v[180:183], v[48:51]
	v_mfma_f32_16x16x32_bf16 v[36:39], v[240:243], v[224:227], v[36:39]
	v_mfma_f32_16x16x32_bf16 v[32:35], v[248:251], v[224:227], v[32:35]
	v_mfma_f32_16x16x32_bf16 v[20:23], v[240:243], v[232:235], v[20:23]
	v_mfma_f32_16x16x32_bf16 v[16:19], v[248:251], v[232:235], v[16:19]
	s_barrier
	ds_read_b128 v[130:133], v217 offset:32768
	ds_read_b128 v[134:137], v217 offset:33792
	ds_read_b128 v[144:147], v217 offset:34816
	ds_read_b128 v[148:151], v217 offset:35840
	s_add_u32 s54, s54, 0x40000
	s_addc_u32 s55, s55, 0
	s_mov_b32 m0, s62
	ds_read_b128 v[156:159], v222 offset:32768
	ds_read_b128 v[160:163], v222 offset:33792
	ds_read_b128 v[164:167], v222 offset:34816
	ds_read_b128 v[180:183], v222 offset:35840
	ds_read_b128 v[184:187], v222 offset:36864
	ds_read_b128 v[224:227], v222 offset:37888
	ds_read_b128 v[228:231], v222 offset:38912
	global_load_lds_dwordx4 v0, s[54:55]
	s_mov_b32 m0, s63
	ds_read_b128 v[232:235], v222 offset:39936
	global_load_lds_dwordx4 v2, s[54:55]
	s_waitcnt lgkmcnt(8)
	s_barrier
	s_waitcnt lgkmcnt(0)
	s_waitcnt lgkmcnt(0)
	v_mfma_f32_16x16x32_bf16 v[152:155], v[130:133], v[156:159], v[152:155]
	v_mfma_f32_16x16x32_bf16 v[138:141], v[144:147], v[156:159], v[138:141]
	v_mfma_f32_16x16x32_bf16 v[116:119], v[130:133], v[164:167], v[116:119]
	v_mfma_f32_16x16x32_bf16 v[112:115], v[144:147], v[164:167], v[112:115]
	v_mfma_f32_16x16x32_bf16 v[100:103], v[130:133], v[184:187], v[100:103]
	v_mfma_f32_16x16x32_bf16 v[96:99], v[144:147], v[184:187], v[96:99]
	v_mfma_f32_16x16x32_bf16 v[84:87], v[130:133], v[228:231], v[84:87]
	v_mfma_f32_16x16x32_bf16 v[80:83], v[144:147], v[228:231], v[80:83]
	v_mfma_f32_16x16x32_bf16 v[152:155], v[134:137], v[160:163], v[152:155]
	v_mfma_f32_16x16x32_bf16 v[140:143], v[148:151], v[160:163], v[138:141]
	v_mfma_f32_16x16x32_bf16 v[116:119], v[134:137], v[180:183], v[116:119]
	v_mfma_f32_16x16x32_bf16 v[112:115], v[148:151], v[180:183], v[112:115]
	v_mfma_f32_16x16x32_bf16 v[100:103], v[134:137], v[224:227], v[100:103]
	v_mfma_f32_16x16x32_bf16 v[96:99], v[148:151], v[224:227], v[96:99]
	v_mfma_f32_16x16x32_bf16 v[84:87], v[134:137], v[232:235], v[84:87]
	v_mfma_f32_16x16x32_bf16 v[80:83], v[148:151], v[232:235], v[80:83]
	s_barrier
	s_add_i32 s54, 0, 0x1c000
	s_add_i32 m0, s59, 0x18000
	ds_read_b128 v[236:239], v217 offset:49152
	ds_read_b128 v[240:243], v217 offset:50176
	ds_read_b128 v[244:247], v217 offset:51200
	ds_read_b128 v[248:251], v217 offset:52224
	s_add_u32 s98, s52, 0x80
	s_addc_u32 s99, s53, 0
	global_load_lds_dwordx4 v0, s[98:99]
	s_add_i32 m0, s59, 0x1a000
	s_nop 0
	global_load_lds_dwordx4 v2, s[98:99]
	s_barrier
	s_waitcnt lgkmcnt(0)
	s_waitcnt lgkmcnt(0)
	v_mfma_f32_16x16x32_bf16 v[124:127], v[236:239], v[156:159], v[124:127]
	v_mfma_f32_16x16x32_bf16 v[120:123], v[244:247], v[156:159], v[120:123]
	v_mfma_f32_16x16x32_bf16 v[108:111], v[236:239], v[164:167], v[108:111]
	v_mfma_f32_16x16x32_bf16 v[104:107], v[244:247], v[164:167], v[104:107]
	v_mfma_f32_16x16x32_bf16 v[92:95], v[236:239], v[184:187], v[92:95]
	v_mfma_f32_16x16x32_bf16 v[88:91], v[244:247], v[184:187], v[88:91]
	v_mfma_f32_16x16x32_bf16 v[76:79], v[236:239], v[228:231], v[76:79]
	v_mfma_f32_16x16x32_bf16 v[72:75], v[244:247], v[228:231], v[72:75]
	v_mfma_f32_16x16x32_bf16 v[124:127], v[240:243], v[160:163], v[124:127]
	v_mfma_f32_16x16x32_bf16 v[120:123], v[248:251], v[160:163], v[120:123]
	v_mfma_f32_16x16x32_bf16 v[108:111], v[240:243], v[180:183], v[108:111]
	v_mfma_f32_16x16x32_bf16 v[104:107], v[248:251], v[180:183], v[104:107]
	v_mfma_f32_16x16x32_bf16 v[92:95], v[240:243], v[224:227], v[92:95]
	v_mfma_f32_16x16x32_bf16 v[88:91], v[248:251], v[224:227], v[88:91]
	v_mfma_f32_16x16x32_bf16 v[76:79], v[240:243], v[232:235], v[76:79]
	v_mfma_f32_16x16x32_bf16 v[72:75], v[248:251], v[232:235], v[72:75]
	s_mov_b32 m0, s64
	s_barrier
	ds_read_b128 v[156:159], v222 offset:49152
	ds_read_b128 v[160:163], v222 offset:50176
	ds_read_b128 v[164:167], v222 offset:51200
	ds_read_b128 v[180:183], v222 offset:52224
	ds_read_b128 v[184:187], v222 offset:53248
	ds_read_b128 v[224:227], v222 offset:54272
	ds_read_b128 v[228:231], v222 offset:55296
	global_load_lds_dwordx4 v0, s[76:77]
	s_mov_b32 m0, s65
	ds_read_b128 v[232:235], v222 offset:56320
	global_load_lds_dwordx4 v2, s[76:77]
	s_barrier
	s_waitcnt lgkmcnt(0)
	s_waitcnt lgkmcnt(0)
	v_mfma_f32_16x16x32_bf16 v[60:63], v[130:133], v[156:159], v[60:63]
	v_mfma_f32_16x16x32_bf16 v[56:59], v[144:147], v[156:159], v[56:59]
	v_mfma_f32_16x16x32_bf16 v[44:47], v[130:133], v[164:167], v[44:47]
	v_mfma_f32_16x16x32_bf16 v[40:43], v[144:147], v[164:167], v[40:43]
	v_mfma_f32_16x16x32_bf16 v[28:31], v[130:133], v[184:187], v[28:31]
	v_mfma_f32_16x16x32_bf16 v[24:27], v[144:147], v[184:187], v[24:27]
	v_mfma_f32_16x16x32_bf16 v[12:15], v[130:133], v[228:231], v[12:15]
	v_mfma_f32_16x16x32_bf16 v[8:11], v[144:147], v[228:231], v[8:11]
	v_mfma_f32_16x16x32_bf16 v[60:63], v[134:137], v[160:163], v[60:63]
	v_mfma_f32_16x16x32_bf16 v[56:59], v[148:151], v[160:163], v[56:59]
	v_mfma_f32_16x16x32_bf16 v[44:47], v[134:137], v[180:183], v[44:47]
	v_mfma_f32_16x16x32_bf16 v[40:43], v[148:151], v[180:183], v[40:43]
	v_mfma_f32_16x16x32_bf16 v[28:31], v[134:137], v[224:227], v[28:31]
	v_mfma_f32_16x16x32_bf16 v[24:27], v[148:151], v[224:227], v[24:27]
	v_mfma_f32_16x16x32_bf16 v[12:15], v[134:137], v[232:235], v[12:15]
	v_mfma_f32_16x16x32_bf16 v[8:11], v[148:151], v[232:235], v[8:11]
	s_barrier
	s_add_u32 s52, s52, 0x40080
	s_addc_u32 s53, s53, 0
	s_add_i32 s26, s54, s59
	s_add_i32 m0, s59, 0x1c000
	s_nop 0
	global_load_lds_dwordx4 v0, s[52:53]
	s_add_i32 m0, s59, 0x1e000
	s_nop 0
	global_load_lds_dwordx4 v2, s[52:53]
	s_add_i32 s72, s72, 2
	s_add_u32 s70, s70, 0x100
	s_addc_u32 s71, s71, 0
	s_add_u32 s50, s50, 0x100
	s_addc_u32 s51, s51, 0
	s_cmp_gt_u32 s72, 13
	s_cbranch_scc1 .LrotX_848
	s_cmp_lg_u32 s72, 12
	s_cselect_b64 s[52:53], -1, 0
	s_add_u32 s26, s50, 0xfffc0080
	s_addc_u32 s54, s51, -1
	s_and_b64 s[52:53], s[52:53], exec
	s_cselect_b32 s55, s54, s25
	s_cselect_b32 s54, s26, s24
	s_cselect_b32 s53, s71, s14
	s_cselect_b32 s52, s70, s15
;     __device__ __forceinline__ void prep(int pm, int par, LAS unsigned char* lds) const { if (fold) prep_rowstats(stat, pm, par, lds); }
;     __device__ __forceinline__ void prep(int pm, int par, LAS unsigned char* lds) const { if (!ident) prep_rowstats(stat, pm, par, lds); }
;     __device__ __forceinline__ void prep(int pm, int par, LAS unsigned char* lds) const { prep_rowstats(stat, pm, par, lds); }
; #define G_STAGE(bufoff, gbase) do { _Pragma("unroll") for (int _i = 0; _i < 2; ++_i) \
;         __builtin_amdgcn_global_load_lds((const unsigned*)((const char*)(gbase) + voff[_i]), (LAS unsigned*)(lds + (bufoff) + ldsw + _i * 8192), 16, 0, 0); } while (0)
; #define G_MMA(ai, bj, At, Bt) do { __builtin_amdgcn_s_setprio(1); _Pragma("unroll") for (int m = 0; m < 4; ++m) _Pragma("unroll") for (int n = 0; n < 2; ++n) _Pragma("unroll") for (int k = 0; k < 2; ++k) \
;         acc[ai][bj][m][n] = MFMA16(Bt[n][k], At[m][k], acc[ai][bj][m][n]); __builtin_amdgcn_s_setprio(0); } while (0)
; #define G_WAIT_V(n) asm volatile("s_waitcnt vmcnt(" #n ")" ::: "memory")
; #define G_BAR __builtin_amdgcn_s_barrier()
; template <class Epi>
; __device__ __forceinline__ void gemm_phase(LAS unsigned char* lds, const bf16_t* Ag, const bf16_t* Btg, const int K, const int nM, const int nN, const Epi& E) {
;     ...
;         for (int t = 0; t < nt; t += 2) {
;             const bool last = (t == nt - 2);
;             const char* a1 = cA + (size_t)(t + 1) * kstep;
;             const char* a2 = last ? nA : cA + (size_t)(t + 2) * kstep; const char* b2 = last ? nB : cB + (size_t)(t + 2) * kstep;
;             const char* a3 = a2 + kstep; const char* b3 = b2 + kstep;
;             if (last && has_next && pmn != pm) E.prep(pmn, par ^ 1, lds);
;     ...
;             G_STAGE(G_SB(1, 1), b3 + hstep);
;             G_WAIT_V(6); G_BAR; G_MMA(1, 1, At, B1); G_BAR;
;         }
.LrotX_848:
	s_waitcnt vmcnt(6)
	s_barrier
	v_mfma_f32_16x16x32_bf16 v[68:71], v[236:239], v[156:159], v[68:71]
	v_mfma_f32_16x16x32_bf16 v[64:67], v[244:247], v[156:159], v[64:67]
	v_mfma_f32_16x16x32_bf16 v[52:55], v[236:239], v[164:167], v[52:55]
	v_mfma_f32_16x16x32_bf16 v[48:51], v[244:247], v[164:167], v[48:51]
	v_mfma_f32_16x16x32_bf16 v[36:39], v[236:239], v[184:187], v[36:39]
	v_mfma_f32_16x16x32_bf16 v[32:35], v[244:247], v[184:187], v[32:35]
	v_mfma_f32_16x16x32_bf16 v[20:23], v[236:239], v[228:231], v[20:23]
	v_mfma_f32_16x16x32_bf16 v[16:19], v[244:247], v[228:231], v[16:19]
	v_mfma_f32_16x16x32_bf16 v[68:71], v[240:243], v[160:163], v[68:71]
	v_mfma_f32_16x16x32_bf16 v[64:67], v[248:251], v[160:163], v[64:67]
	v_mfma_f32_16x16x32_bf16 v[52:55], v[240:243], v[180:183], v[52:55]
	v_mfma_f32_16x16x32_bf16 v[48:51], v[248:251], v[180:183], v[48:51]
	v_mfma_f32_16x16x32_bf16 v[36:39], v[240:243], v[224:227], v[36:39]
	v_mfma_f32_16x16x32_bf16 v[32:35], v[248:251], v[224:227], v[32:35]
	v_mfma_f32_16x16x32_bf16 v[20:23], v[240:243], v[232:235], v[20:23]
	v_mfma_f32_16x16x32_bf16 v[16:19], v[248:251], v[232:235], v[16:19]
	s_cmp_gt_u32 s72, 13
	s_barrier
	s_cbranch_scc1 .LBB0_852
	s_cmp_lg_u32 s72, 12
	s_cbranch_scc1 .LmainW_848
